# v78 + s_setprio 1 on sample-attention compute waves + back-edge rotation (loop-control SALU moved ahead of the closing barrier) in the four GEMM K-loops
# baseline (speedup 1.0000x reference)
; #define PG8_STAGE(bufoff, gbase, voff) do { _Pragma("unroll") for (int _i = 0; _i < 2; ++_i) \
;         __builtin_amdgcn_global_load_lds((const unsigned*)((const char*)(gbase) + (voff)[_i]), (PG8_LAS unsigned*)(lds + (bufoff) + ldsw + _i * 8192), 16, 0, 0); } while (0)
; #define PG8_LDA(dst, b, h) do { _Pragma("unroll") for (int m = 0; m < 4; ++m) _Pragma("unroll") for (int k = 0; k < 2; ++k) dst[m][k] = *(const PG8_LAS bf16x8*)(lds + PG8_SA(b, h) + aoff + m * 2048 + k * 1024); } while (0)
; #define PG8_LDB(dst, b, h) do { _Pragma("unroll") for (int n = 0; n < 2; ++n) _Pragma("unroll") for (int k = 0; k < 2; ++k) dst[n][k] = *(const PG8_LAS bf16x8*)(lds + PG8_SB(b, h) + boff + n * 2048 + k * 1024); } while (0)
; #define PG8_MMA(ai, bj, At, Bt) do { __builtin_amdgcn_s_setprio(1); _Pragma("unroll") for (int m = 0; m < 4; ++m) _Pragma("unroll") for (int n = 0; n < 2; ++n) _Pragma("unroll") for (int k = 0; k < 2; ++k) \
;         acc[ai][bj][m][n] = __builtin_amdgcn_mfma_f32_16x16x32_bf16(Bt[n][k], At[m][k], acc[ai][bj][m][n], 0, 0, 0); __builtin_amdgcn_s_setprio(0); } while (0)
; #define PG8_WAIT_V(n) asm volatile("s_waitcnt vmcnt(" #n ")" ::: "memory")
; #define PG8_WAIT_L(n) asm volatile("s_waitcnt lgkmcnt(" #n ")" ::: "memory")
; #define PG8_BAR __builtin_amdgcn_s_barrier()
; #define PG8_SCHED __builtin_amdgcn_sched_barrier(0)
; template <class Epi, class Sched, bool ALIGN_EPI = false, bool SP2 = false>
; __device__ __forceinline__ void gemm_phase(PG8_LAS unsigned char* lds, const Gemm g, const Sched& S, const Epi& E) {
;     ...
;             if constexpr (SP2) {
;             PG8_LDB(B0, 0, 0); PG8_LDB(B1, 0, 1); PG8_SCHED; PG8_LDA(At, 0, 0); PG8_STAGE(PG8_SA(1, 1), a1 + hstep, voffA);
;             PG8_WAIT_V(8); PG8_WAIT_L(0); PG8_BAR; PG8_MMA(0, 0, At, B0); PG8_MMA(0, 1, At, B1); PG8_BAR; PG8_SCHED;
;             PG8_LDA(At, 0, 1); PG8_STAGE(PG8_SB(0, 0), b2, voffB); PG8_STAGE(PG8_SB(0, 1), b2 + hstep, voffB); PG8_STAGE(PG8_SA(0, 0), a2, voffA);
;             PG8_WAIT_V(8); PG8_WAIT_L(0); PG8_BAR; PG8_MMA(1, 0, At, B0); PG8_MMA(1, 1, At, B1); PG8_BAR; PG8_SCHED;
.LBB0_159:
	s_add_u32 s24, s22, 0xfffc0080
	s_addc_u32 s25, s23, -1
	s_add_i32 s66, 0, 0x10000
	s_cmp_eq_u32 s65, 12
	s_cselect_b32 s27, s9, s25
	s_cselect_b32 s26, s17, s24
	v_add_u32_e32 v156, s66, v145
	s_cselect_b32 s25, s15, s64
	s_cselect_b32 s24, s54, s55
	s_add_i32 s72, 0, 0x14000
	ds_read_b128 v[132:135], v156
	ds_read_b128 v[152:155], v156 offset:1024
	ds_read_b128 v[160:163], v156 offset:2048
	ds_read_b128 v[164:167], v156 offset:3072
	v_add_u32_e32 v156, s72, v145
	ds_read_b128 v[168:171], v156
	ds_read_b128 v[172:175], v156 offset:1024
	ds_read_b128 v[176:179], v156 offset:2048
	ds_read_b128 v[180:183], v156 offset:3072
	v_lshl_add_u64 v[156:157], s[22:23], 0, v[148:149]
	s_add_i32 m0, s37, 0xc000
	ds_read_b128 v[184:187], v159
	ds_read_b128 v[188:191], v159 offset:1024
	ds_read_b128 v[192:195], v159 offset:2048
	ds_read_b128 v[210:213], v159 offset:3072
	ds_read_b128 v[214:217], v159 offset:4096
	ds_read_b128 v[218:221], v159 offset:5120
	ds_read_b128 v[222:225], v159 offset:6144
	ds_read_b128 v[226:229], v159 offset:7168
	global_load_lds_dwordx4 v[156:157], off
	v_lshl_add_u64 v[156:157], s[22:23], 0, v[150:151]
	s_add_i32 m0, s37, 0xe000
	s_nop 0
	global_load_lds_dwordx4 v[156:157], off
	s_waitcnt vmcnt(8)
	s_waitcnt lgkmcnt(0)
	s_barrier
	s_setprio 1
	s_waitcnt lgkmcnt(0)
	v_mfma_f32_16x16x32_bf16 v[128:131], v[132:135], v[184:187], v[128:131]
	v_mfma_f32_16x16x32_bf16 v[124:127], v[160:163], v[184:187], v[124:127]
	v_mfma_f32_16x16x32_bf16 v[112:115], v[132:135], v[192:195], v[112:115]
	v_mfma_f32_16x16x32_bf16 v[108:111], v[160:163], v[192:195], v[108:111]
	v_mfma_f32_16x16x32_bf16 v[96:99], v[132:135], v[214:217], v[96:99]
	v_mfma_f32_16x16x32_bf16 v[92:95], v[160:163], v[214:217], v[92:95]
	v_mfma_f32_16x16x32_bf16 v[80:83], v[132:135], v[222:225], v[80:83]
	v_mfma_f32_16x16x32_bf16 v[76:79], v[160:163], v[222:225], v[76:79]
	v_mfma_f32_16x16x32_bf16 v[128:131], v[152:155], v[188:191], v[128:131]
	v_mfma_f32_16x16x32_bf16 v[124:127], v[164:167], v[188:191], v[124:127]
	v_mfma_f32_16x16x32_bf16 v[112:115], v[152:155], v[210:213], v[112:115]
	v_mfma_f32_16x16x32_bf16 v[108:111], v[164:167], v[210:213], v[108:111]
	v_mfma_f32_16x16x32_bf16 v[96:99], v[152:155], v[218:221], v[96:99]
	v_mfma_f32_16x16x32_bf16 v[92:95], v[164:167], v[218:221], v[92:95]
	v_mfma_f32_16x16x32_bf16 v[80:83], v[152:155], v[226:229], v[80:83]
	v_mfma_f32_16x16x32_bf16 v[76:79], v[164:167], v[226:229], v[76:79]
	s_setprio 0
	s_setprio 1
	v_mfma_f32_16x16x32_bf16 v[120:123], v[168:171], v[184:187], v[120:123]
	v_mfma_f32_16x16x32_bf16 v[116:119], v[176:179], v[184:187], v[116:119]
	v_mfma_f32_16x16x32_bf16 v[104:107], v[168:171], v[192:195], v[104:107]
	v_mfma_f32_16x16x32_bf16 v[100:103], v[176:179], v[192:195], v[100:103]
	v_mfma_f32_16x16x32_bf16 v[88:91], v[168:171], v[214:217], v[88:91]
	v_mfma_f32_16x16x32_bf16 v[84:87], v[176:179], v[214:217], v[84:87]
	v_mfma_f32_16x16x32_bf16 v[72:75], v[168:171], v[222:225], v[72:75]
	v_mfma_f32_16x16x32_bf16 v[68:71], v[176:179], v[222:225], v[68:71]
	v_mfma_f32_16x16x32_bf16 v[120:123], v[172:175], v[188:191], v[120:123]
	v_mfma_f32_16x16x32_bf16 v[116:119], v[180:183], v[188:191], v[116:119]
	v_mfma_f32_16x16x32_bf16 v[104:107], v[172:175], v[210:213], v[104:107]
	v_mfma_f32_16x16x32_bf16 v[100:103], v[180:183], v[210:213], v[100:103]
	v_mfma_f32_16x16x32_bf16 v[88:91], v[172:175], v[218:221], v[88:91]
	v_mfma_f32_16x16x32_bf16 v[84:87], v[180:183], v[218:221], v[84:87]
	v_mfma_f32_16x16x32_bf16 v[72:75], v[172:175], v[226:229], v[72:75]
	v_mfma_f32_16x16x32_bf16 v[68:71], v[180:183], v[226:229], v[68:71]
	s_setprio 0
	s_barrier
	s_add_i32 s66, s66, s30
	v_lshl_add_u64 v[156:157], s[24:25], 0, v[138:139]
	s_mov_b32 m0, s66
	ds_read_b128 v[184:187], v159 offset:16384
	ds_read_b128 v[188:191], v159 offset:17408
	ds_read_b128 v[192:195], v159 offset:18432
	ds_read_b128 v[210:213], v159 offset:19456
	ds_read_b128 v[214:217], v159 offset:20480
	ds_read_b128 v[218:221], v159 offset:21504
	ds_read_b128 v[222:225], v159 offset:22528
	ds_read_b128 v[226:229], v159 offset:23552
	global_load_lds_dwordx4 v[156:157], off
	s_add_i32 m0, s66, 0x2000
	s_add_u32 s66, s24, 0x40000
	v_lshl_add_u64 v[246:247], s[24:25], 0, v[142:143]
	s_addc_u32 s67, s25, 0
	s_add_i32 s72, s72, s30
	global_load_lds_dwordx4 v[246:247], off
	v_lshl_add_u64 v[248:249], s[66:67], 0, v[138:139]
	s_mov_b32 m0, s72
	v_lshl_add_u64 v[250:251], s[26:27], 0, v[140:141]
	global_load_lds_dwordx4 v[248:249], off
	v_lshl_add_u64 v[248:249], s[66:67], 0, v[142:143]
	s_add_i32 m0, s72, 0x2000
	s_nop 0
	global_load_lds_dwordx4 v[248:249], off
	v_lshl_add_u64 v[248:249], s[26:27], 0, v[136:137]
	s_mov_b32 m0, s37
	s_nop 0
	global_load_lds_dwordx4 v[248:249], off
	s_mov_b32 m0, s44
	s_nop 0
	global_load_lds_dwordx4 v[250:251], off
	s_waitcnt vmcnt(8)
	s_waitcnt lgkmcnt(0)
	s_barrier
; #define PG8_STAGE(bufoff, gbase, voff) do { _Pragma("unroll") for (int _i = 0; _i < 2; ++_i) \
;         __builtin_amdgcn_global_load_lds((const unsigned*)((const char*)(gbase) + (voff)[_i]), (PG8_LAS unsigned*)(lds + (bufoff) + ldsw + _i * 8192), 16, 0, 0); } while (0)
; #define PG8_LDA(dst, b, h) do { _Pragma("unroll") for (int m = 0; m < 4; ++m) _Pragma("unroll") for (int k = 0; k < 2; ++k) dst[m][k] = *(const PG8_LAS bf16x8*)(lds + PG8_SA(b, h) + aoff + m * 2048 + k * 1024); } while (0)
; #define PG8_LDB(dst, b, h) do { _Pragma("unroll") for (int n = 0; n < 2; ++n) _Pragma("unroll") for (int k = 0; k < 2; ++k) dst[n][k] = *(const PG8_LAS bf16x8*)(lds + PG8_SB(b, h) + boff + n * 2048 + k * 1024); } while (0)
; #define PG8_MMA(ai, bj, At, Bt) do { __builtin_amdgcn_s_setprio(1); _Pragma("unroll") for (int m = 0; m < 4; ++m) _Pragma("unroll") for (int n = 0; n < 2; ++n) _Pragma("unroll") for (int k = 0; k < 2; ++k) \
;         acc[ai][bj][m][n] = __builtin_amdgcn_mfma_f32_16x16x32_bf16(Bt[n][k], At[m][k], acc[ai][bj][m][n], 0, 0, 0); __builtin_amdgcn_s_setprio(0); } while (0)
; #define PG8_WAIT_V(n) asm volatile("s_waitcnt vmcnt(" #n ")" ::: "memory")
; #define PG8_WAIT_L(n) asm volatile("s_waitcnt lgkmcnt(" #n ")" ::: "memory")
; #define PG8_BAR __builtin_amdgcn_s_barrier()
; #define PG8_SCHED __builtin_amdgcn_sched_barrier(0)
; template <class Epi, class Sched, bool ALIGN_EPI = false, bool SP2 = false>
; __device__ __forceinline__ void gemm_phase(PG8_LAS unsigned char* lds, const Gemm g, const Sched& S, const Epi& E) {
;     ...
;             PG8_LDA(At, 0, 1); PG8_STAGE(PG8_SB(0, 0), b2, voffB); PG8_STAGE(PG8_SB(0, 1), b2 + hstep, voffB); PG8_STAGE(PG8_SA(0, 0), a2, voffA);
;             PG8_WAIT_V(8); PG8_WAIT_L(0); PG8_BAR; PG8_MMA(1, 0, At, B0); PG8_MMA(1, 1, At, B1); PG8_BAR; PG8_SCHED;
;             PG8_LDB(B0, 1, 0); PG8_LDB(B1, 1, 1); PG8_SCHED; PG8_LDA(At, 1, 0); PG8_STAGE(PG8_SA(0, 1), a2 + hstep, voffA);
;             PG8_WAIT_V(8); PG8_WAIT_L(0); PG8_BAR; PG8_MMA(0, 0, At, B0); PG8_MMA(0, 1, At, B1); PG8_BAR; PG8_SCHED;
	s_setprio 1
	s_waitcnt lgkmcnt(0)
	v_mfma_f32_16x16x32_bf16 v[64:67], v[132:135], v[184:187], v[64:67]
	v_mfma_f32_16x16x32_bf16 v[60:63], v[160:163], v[184:187], v[60:63]
	v_mfma_f32_16x16x32_bf16 v[48:51], v[132:135], v[192:195], v[48:51]
	v_mfma_f32_16x16x32_bf16 v[44:47], v[160:163], v[192:195], v[44:47]
	v_mfma_f32_16x16x32_bf16 v[32:35], v[132:135], v[214:217], v[32:35]
	v_mfma_f32_16x16x32_bf16 v[28:31], v[160:163], v[214:217], v[28:31]
	v_mfma_f32_16x16x32_bf16 v[16:19], v[132:135], v[222:225], v[16:19]
	v_mfma_f32_16x16x32_bf16 v[12:15], v[160:163], v[222:225], v[12:15]
	v_mfma_f32_16x16x32_bf16 v[64:67], v[152:155], v[188:191], v[64:67]
	v_mfma_f32_16x16x32_bf16 v[60:63], v[164:167], v[188:191], v[60:63]
	v_mfma_f32_16x16x32_bf16 v[48:51], v[152:155], v[210:213], v[48:51]
	v_mfma_f32_16x16x32_bf16 v[44:47], v[164:167], v[210:213], v[44:47]
	v_mfma_f32_16x16x32_bf16 v[32:35], v[152:155], v[218:221], v[32:35]
	v_mfma_f32_16x16x32_bf16 v[28:31], v[164:167], v[218:221], v[28:31]
	v_mfma_f32_16x16x32_bf16 v[16:19], v[152:155], v[226:229], v[16:19]
	v_mfma_f32_16x16x32_bf16 v[12:15], v[164:167], v[226:229], v[12:15]
	s_setprio 0
	s_setprio 1
	v_mfma_f32_16x16x32_bf16 v[56:59], v[168:171], v[184:187], v[56:59]
	v_mfma_f32_16x16x32_bf16 v[52:55], v[176:179], v[184:187], v[52:55]
	v_mfma_f32_16x16x32_bf16 v[40:43], v[168:171], v[192:195], v[40:43]
	v_mfma_f32_16x16x32_bf16 v[36:39], v[176:179], v[192:195], v[36:39]
	v_mfma_f32_16x16x32_bf16 v[24:27], v[168:171], v[214:217], v[24:27]
	v_mfma_f32_16x16x32_bf16 v[20:23], v[176:179], v[214:217], v[20:23]
	v_mfma_f32_16x16x32_bf16 v[8:11], v[168:171], v[222:225], v[8:11]
	v_mfma_f32_16x16x32_bf16 v[4:7], v[176:179], v[222:225], v[4:7]
	v_mfma_f32_16x16x32_bf16 v[56:59], v[172:175], v[188:191], v[56:59]
	v_mfma_f32_16x16x32_bf16 v[52:55], v[180:183], v[188:191], v[52:55]
	v_mfma_f32_16x16x32_bf16 v[40:43], v[172:175], v[210:213], v[40:43]
	v_mfma_f32_16x16x32_bf16 v[36:39], v[180:183], v[210:213], v[36:39]
	v_mfma_f32_16x16x32_bf16 v[24:27], v[172:175], v[218:221], v[24:27]
	v_mfma_f32_16x16x32_bf16 v[20:23], v[180:183], v[218:221], v[20:23]
	v_mfma_f32_16x16x32_bf16 v[8:11], v[172:175], v[226:229], v[8:11]
	v_mfma_f32_16x16x32_bf16 v[4:7], v[180:183], v[226:229], v[4:7]
	s_setprio 0
	s_barrier
	s_add_i32 s66, 0, 0x18000
	s_add_i32 s67, 0, 0x1c000
	v_add_u32_e32 v164, s66, v145
	v_add_u32_e32 v180, s67, v145
	ds_read_b128 v[132:135], v164
	ds_read_b128 v[152:155], v164 offset:1024
	ds_read_b128 v[160:163], v164 offset:2048
	ds_read_b128 v[164:167], v164 offset:3072
	ds_read_b128 v[168:171], v180
	ds_read_b128 v[172:175], v180 offset:1024
	ds_read_b128 v[176:179], v180 offset:2048
	ds_read_b128 v[180:183], v180 offset:3072
	s_add_u32 s26, s26, 0x40000
	s_addc_u32 s27, s27, 0
	s_mov_b32 m0, s45
	v_lshl_add_u64 v[252:253], s[26:27], 0, v[136:137]
	ds_read_b128 v[184:187], v159 offset:32768
	ds_read_b128 v[188:191], v159 offset:33792
	ds_read_b128 v[192:195], v159 offset:34816
	ds_read_b128 v[210:213], v159 offset:35840
	ds_read_b128 v[214:217], v159 offset:36864
	ds_read_b128 v[218:221], v159 offset:37888
	ds_read_b128 v[222:225], v159 offset:38912
	ds_read_b128 v[226:229], v159 offset:39936
	global_load_lds_dwordx4 v[252:253], off
	v_lshl_add_u64 v[252:253], s[26:27], 0, v[140:141]
	s_mov_b32 m0, s48
	s_nop 0
	global_load_lds_dwordx4 v[252:253], off
	s_waitcnt vmcnt(8)
	s_waitcnt lgkmcnt(0)
	s_barrier
	s_setprio 1
	s_waitcnt lgkmcnt(0)
	v_mfma_f32_16x16x32_bf16 v[128:131], v[132:135], v[184:187], v[128:131]
	v_mfma_f32_16x16x32_bf16 v[124:127], v[160:163], v[184:187], v[124:127]
	v_mfma_f32_16x16x32_bf16 v[112:115], v[132:135], v[192:195], v[112:115]
	v_mfma_f32_16x16x32_bf16 v[108:111], v[160:163], v[192:195], v[108:111]
	v_mfma_f32_16x16x32_bf16 v[96:99], v[132:135], v[214:217], v[96:99]
	v_mfma_f32_16x16x32_bf16 v[92:95], v[160:163], v[214:217], v[92:95]
	v_mfma_f32_16x16x32_bf16 v[80:83], v[132:135], v[222:225], v[80:83]
	v_mfma_f32_16x16x32_bf16 v[76:79], v[160:163], v[222:225], v[76:79]
	v_mfma_f32_16x16x32_bf16 v[128:131], v[152:155], v[188:191], v[128:131]
	v_mfma_f32_16x16x32_bf16 v[124:127], v[164:167], v[188:191], v[124:127]
	v_mfma_f32_16x16x32_bf16 v[112:115], v[152:155], v[210:213], v[112:115]
	v_mfma_f32_16x16x32_bf16 v[108:111], v[164:167], v[210:213], v[108:111]
	v_mfma_f32_16x16x32_bf16 v[96:99], v[152:155], v[218:221], v[96:99]
	v_mfma_f32_16x16x32_bf16 v[92:95], v[164:167], v[218:221], v[92:95]
	v_mfma_f32_16x16x32_bf16 v[80:83], v[152:155], v[226:229], v[80:83]
	v_mfma_f32_16x16x32_bf16 v[76:79], v[164:167], v[226:229], v[76:79]
	s_setprio 0
	s_setprio 1
	v_mfma_f32_16x16x32_bf16 v[120:123], v[168:171], v[184:187], v[120:123]
	v_mfma_f32_16x16x32_bf16 v[116:119], v[176:179], v[184:187], v[116:119]
	v_mfma_f32_16x16x32_bf16 v[104:107], v[168:171], v[192:195], v[104:107]
	v_mfma_f32_16x16x32_bf16 v[100:103], v[176:179], v[192:195], v[100:103]
	v_mfma_f32_16x16x32_bf16 v[88:91], v[168:171], v[214:217], v[88:91]
	v_mfma_f32_16x16x32_bf16 v[84:87], v[176:179], v[214:217], v[84:87]
	v_mfma_f32_16x16x32_bf16 v[72:75], v[168:171], v[222:225], v[72:75]
	v_mfma_f32_16x16x32_bf16 v[68:71], v[176:179], v[222:225], v[68:71]
	v_mfma_f32_16x16x32_bf16 v[120:123], v[172:175], v[188:191], v[120:123]
	v_mfma_f32_16x16x32_bf16 v[116:119], v[180:183], v[188:191], v[116:119]
	v_mfma_f32_16x16x32_bf16 v[104:107], v[172:175], v[210:213], v[104:107]
	v_mfma_f32_16x16x32_bf16 v[100:103], v[180:183], v[210:213], v[100:103]
	v_mfma_f32_16x16x32_bf16 v[88:91], v[172:175], v[218:221], v[88:91]
	v_mfma_f32_16x16x32_bf16 v[84:87], v[180:183], v[218:221], v[84:87]
	v_mfma_f32_16x16x32_bf16 v[72:75], v[172:175], v[226:229], v[72:75]
	v_mfma_f32_16x16x32_bf16 v[68:71], v[180:183], v[226:229], v[68:71]
	s_setprio 0
	s_barrier
; #define PG8_STAGE(bufoff, gbase, voff) do { _Pragma("unroll") for (int _i = 0; _i < 2; ++_i) \
;         __builtin_amdgcn_global_load_lds((const unsigned*)((const char*)(gbase) + (voff)[_i]), (PG8_LAS unsigned*)(lds + (bufoff) + ldsw + _i * 8192), 16, 0, 0); } while (0)
; #define PG8_LDA(dst, b, h) do { _Pragma("unroll") for (int m = 0; m < 4; ++m) _Pragma("unroll") for (int k = 0; k < 2; ++k) dst[m][k] = *(const PG8_LAS bf16x8*)(lds + PG8_SA(b, h) + aoff + m * 2048 + k * 1024); } while (0)
; #define PG8_MMA(ai, bj, At, Bt) do { __builtin_amdgcn_s_setprio(1); _Pragma("unroll") for (int m = 0; m < 4; ++m) _Pragma("unroll") for (int n = 0; n < 2; ++n) _Pragma("unroll") for (int k = 0; k < 2; ++k) \
;         acc[ai][bj][m][n] = __builtin_amdgcn_mfma_f32_16x16x32_bf16(Bt[n][k], At[m][k], acc[ai][bj][m][n], 0, 0, 0); __builtin_amdgcn_s_setprio(0); } while (0)
; #define PG8_WAIT_V(n) asm volatile("s_waitcnt vmcnt(" #n ")" ::: "memory")
; #define PG8_WAIT_L(n) asm volatile("s_waitcnt lgkmcnt(" #n ")" ::: "memory")
; #define PG8_BAR __builtin_amdgcn_s_barrier()
; #define PG8_SCHED __builtin_amdgcn_sched_barrier(0)
; template <class Epi, class Sched, bool ALIGN_EPI = false, bool SP2 = false>
; __device__ __forceinline__ void gemm_phase(PG8_LAS unsigned char* lds, const Gemm g, const Sched& S, const Epi& E) {
;     ...
;             PG8_WAIT_V(8); PG8_WAIT_L(0); PG8_BAR; PG8_MMA(0, 0, At, B0); PG8_MMA(0, 1, At, B1); PG8_BAR; PG8_SCHED;
;             PG8_LDA(At, 1, 1); PG8_STAGE(PG8_SB(1, 0), b3, voffB); PG8_STAGE(PG8_SB(1, 1), b3 + hstep, voffB); PG8_STAGE(PG8_SA(1, 0), a3, voffA);
;             PG8_WAIT_V(8); PG8_WAIT_L(0); PG8_BAR; PG8_MMA(1, 0, At, B0); PG8_MMA(1, 1, At, B1); PG8_BAR; PG8_SCHED;
	s_add_i32 s26, s66, s30
	v_lshl_add_u64 v[156:157], v[156:157], 0, s[78:79]
	s_mov_b32 m0, s26
	ds_read_b128 v[184:187], v159 offset:49152
	ds_read_b128 v[188:191], v159 offset:50176
	ds_read_b128 v[192:195], v159 offset:51200
	ds_read_b128 v[210:213], v159 offset:52224
	ds_read_b128 v[214:217], v159 offset:53248
	ds_read_b128 v[218:221], v159 offset:54272
	ds_read_b128 v[222:225], v159 offset:55296
	ds_read_b128 v[226:229], v159 offset:56320
	global_load_lds_dwordx4 v[156:157], off
	s_add_i32 m0, s26, 0x2000
	s_add_u32 s24, s24, 0x40080
	v_lshl_add_u64 v[156:157], v[246:247], 0, s[78:79]
	s_addc_u32 s25, s25, 0
	s_add_i32 s26, s67, s30
	global_load_lds_dwordx4 v[156:157], off
	v_lshl_add_u64 v[156:157], s[24:25], 0, v[138:139]
	s_mov_b32 m0, s26
	s_nop 0
	global_load_lds_dwordx4 v[156:157], off
	v_lshl_add_u64 v[156:157], s[24:25], 0, v[142:143]
	s_add_i32 m0, s26, 0x2000
	s_nop 0
	global_load_lds_dwordx4 v[156:157], off
	v_lshl_add_u64 v[156:157], v[248:249], 0, s[78:79]
	s_mov_b32 m0, s49
	s_nop 0
	global_load_lds_dwordx4 v[156:157], off
	v_lshl_add_u64 v[156:157], v[250:251], 0, s[78:79]
	s_mov_b32 m0, s52
	s_nop 0
	global_load_lds_dwordx4 v[156:157], off
	s_waitcnt vmcnt(8)
	s_waitcnt lgkmcnt(0)
	s_barrier
	s_setprio 1
	s_waitcnt lgkmcnt(0)
	v_mfma_f32_16x16x32_bf16 v[64:67], v[132:135], v[184:187], v[64:67]
	v_mfma_f32_16x16x32_bf16 v[60:63], v[160:163], v[184:187], v[60:63]
	v_mfma_f32_16x16x32_bf16 v[48:51], v[132:135], v[192:195], v[48:51]
	v_mfma_f32_16x16x32_bf16 v[44:47], v[160:163], v[192:195], v[44:47]
	v_mfma_f32_16x16x32_bf16 v[32:35], v[132:135], v[214:217], v[32:35]
	v_mfma_f32_16x16x32_bf16 v[28:31], v[160:163], v[214:217], v[28:31]
	v_mfma_f32_16x16x32_bf16 v[16:19], v[132:135], v[222:225], v[16:19]
	v_mfma_f32_16x16x32_bf16 v[12:15], v[160:163], v[222:225], v[12:15]
	v_mfma_f32_16x16x32_bf16 v[64:67], v[152:155], v[188:191], v[64:67]
	v_mfma_f32_16x16x32_bf16 v[60:63], v[164:167], v[188:191], v[60:63]
	v_mfma_f32_16x16x32_bf16 v[48:51], v[152:155], v[210:213], v[48:51]
	v_mfma_f32_16x16x32_bf16 v[44:47], v[164:167], v[210:213], v[44:47]
	v_mfma_f32_16x16x32_bf16 v[32:35], v[152:155], v[218:221], v[32:35]
	v_mfma_f32_16x16x32_bf16 v[28:31], v[164:167], v[218:221], v[28:31]
	v_mfma_f32_16x16x32_bf16 v[16:19], v[152:155], v[226:229], v[16:19]
	v_mfma_f32_16x16x32_bf16 v[12:15], v[164:167], v[226:229], v[12:15]
	s_setprio 0
	s_setprio 1
	v_mfma_f32_16x16x32_bf16 v[56:59], v[168:171], v[184:187], v[56:59]
	v_mfma_f32_16x16x32_bf16 v[52:55], v[176:179], v[184:187], v[52:55]
	v_mfma_f32_16x16x32_bf16 v[40:43], v[168:171], v[192:195], v[40:43]
	v_mfma_f32_16x16x32_bf16 v[36:39], v[176:179], v[192:195], v[36:39]
	v_mfma_f32_16x16x32_bf16 v[24:27], v[168:171], v[214:217], v[24:27]
	v_mfma_f32_16x16x32_bf16 v[20:23], v[176:179], v[214:217], v[20:23]
	v_mfma_f32_16x16x32_bf16 v[8:11], v[168:171], v[222:225], v[8:11]
	v_mfma_f32_16x16x32_bf16 v[4:7], v[176:179], v[222:225], v[4:7]
	v_mfma_f32_16x16x32_bf16 v[56:59], v[172:175], v[188:191], v[56:59]
	v_mfma_f32_16x16x32_bf16 v[52:55], v[180:183], v[188:191], v[52:55]
	v_mfma_f32_16x16x32_bf16 v[40:43], v[172:175], v[210:213], v[40:43]
	v_mfma_f32_16x16x32_bf16 v[36:39], v[180:183], v[210:213], v[36:39]
	v_mfma_f32_16x16x32_bf16 v[24:27], v[172:175], v[218:221], v[24:27]
	v_mfma_f32_16x16x32_bf16 v[20:23], v[180:183], v[218:221], v[20:23]
	v_mfma_f32_16x16x32_bf16 v[8:11], v[172:175], v[226:229], v[8:11]
	v_mfma_f32_16x16x32_bf16 v[4:7], v[180:183], v[226:229], v[4:7]
	s_setprio 0
	s_add_i32 s65, s65, 2
	s_add_u32 s22, s22, 0x100
	s_addc_u32 s23, s23, 0
	s_add_u32 s55, s55, 0x100
	s_addc_u32 s64, s64, 0
	s_cmp_gt_u32 s65, 13
	s_barrier
	s_cbranch_scc0 .LBB0_159
	s_and_b64 vcc, exec, s[10:11]
	s_cbranch_vccz .LBB0_162
	s_barrier

; #define LAS __attribute__((address_space(3)))
; __device__ __forceinline__ int fresh_tid() { int t = threadIdx.x; asm volatile("" : "+v"(t)); return t; }
; __device__ __forceinline__ int v_rd_base(int lane) { return ((lane & 3) << 3) | (((lane >> 2) & 3) << 6) | (((lane >> 4) & 1) << 5) | (((lane >> 5) & 1) << 8); }
; #define BARRIER1() asm volatile("s_waitcnt lgkmcnt(0)\n\ts_barrier" ::: "memory")
; __device__ __forceinline__ void attn_unit_sample(LAS unsigned char* lds, const float* Kg, const float* Vg, const float* Kl, const float* Vl, const bf16* Qrow0, bf16* Orow0,
;                                                  int qpos0, int h, const float* gnorm) {
;   using St = Stage<true>; constexpr int LDK = 512, NT = 65;
;   const int tid = fresh_tid(), wid = __builtin_amdgcn_readfirstlane(tid >> 6), lane = tid & 63, r32 = lane & 31, hi = lane >> 5;
;   const int g = wid & 1, rb = (wid >> 1) & 1; const bool live = wid < 4;
;   LAS char* V_lds = (LAS char*)lds + OFF_V; LAS char* K_lds = (LAS char*)lds + OFF_K;
;   LAS float* wsf = (LAS float*)(lds + OFF_WS) + wid * 64; LAS float* li_l = wsf; LAS float* al_l = wsf + 32;
;   const LAS float* tab = (const LAS float*)(lds + OFF_TAB) + h * TAB_N;
;   float l_reg = 0; f32x16 o[4] = {};
;     ...
;   if (!live) {
;     const int lt = tid - 256, sr = lt >> 4, sc = (lt & 15) * 8;
;     typename St::T A[8], B[8], C[8];
;     ...
;     LLOAD(A, 0); LLOAD(B, 1); LLOAD(C, 2);
;     asm volatile("s_waitcnt vmcnt(32)" ::: "memory"); LWRITE(A, 0); BARRIER1();
;     for (int t = 0; t < NT; t += 6) {
;       LSTEP(t, A, B, 1);     if (t + 1 >= NT) break;
;       LSTEP(t + 1, B, C, 0); if (t + 2 >= NT) break;
;       LSTEP(t + 2, C, A, 1); if (t + 3 >= NT) break;
;       LSTEP(t + 3, A, B, 0); if (t + 4 >= NT) break;
;       LSTEP(t + 4, B, C, 1); if (t + 5 >= NT) break;
;       LSTEP(t + 5, C, A, 0);
;     }
;     ...
;   } else {
;     float m_reg = -1e30f; bf16x8 qr[4];
;     const bf16* Qw = Qrow0 + (size_t)(rb * 32 + r32) * 3328 + g * 64 + hi * 8;
; #pragma unroll
;     for (int d0 = 0; d0 < 4; ++d0) qr[d0] = *reinterpret_cast<const bf16x8*>(Qw + d0 * 16);
;     const int qpos = qpos0 + rb * 32 + r32;
;     const LAS char* vb0 = V_lds + v_rd_base(lane);
;     BARRIER1();
;     for (int j = 0; j < NT; ++j) { const int bsel = j & 1;
.LBB0_668:
	s_lshl_b32 s0, s20, 6
	s_add_i32 s72, s0, 0x4000
	s_and_b32 s0, s23, 0x3fffffc0
	s_lshl_b32 s0, s0, 2
	s_waitcnt vmcnt(3)
	v_and_b32_e32 v118, 63, v3
	v_and_b32_e32 v116, 31, v3
	s_add_i32 s20, s0, 0
	v_bfe_u32 v3, v3, 5, 1
	s_and_b32 s13, s24, 1
	s_bfe_u32 s12, s23, 0x10007
	s_add_i32 s20, s20, 0x1c000
	v_mov_b32_e32 v19, 0
	s_and_b64 vcc, exec, s[10:11]
	v_cmp_gt_u32_e64 s[6:7], 32, v118
	v_lshlrev_b32_e32 v117, 2, v116
	v_mov_b32_e32 v18, 0
	v_mov_b32_e32 v17, 0
	v_mov_b32_e32 v16, 0
	v_mov_b32_e32 v15, 0
	v_mov_b32_e32 v14, 0
	v_mov_b32_e32 v13, 0
	v_mov_b32_e32 v12, 0
	v_mov_b32_e32 v11, 0
	v_mov_b32_e32 v10, 0
	v_mov_b32_e32 v9, 0
	v_mov_b32_e32 v8, 0
	v_mov_b32_e32 v7, 0
	v_mov_b32_e32 v6, 0
	v_mov_b32_e32 v5, 0
	v_mov_b32_e32 v4, 0
	v_mov_b32_e32 v35, 0
	v_mov_b32_e32 v34, 0
	v_mov_b32_e32 v33, 0
	v_mov_b32_e32 v32, 0
	v_mov_b32_e32 v31, 0
	v_mov_b32_e32 v30, 0
	v_mov_b32_e32 v29, 0
	v_mov_b32_e32 v28, 0
	v_mov_b32_e32 v27, 0
	v_mov_b32_e32 v26, 0
	v_mov_b32_e32 v25, 0
	v_mov_b32_e32 v24, 0
	v_mov_b32_e32 v23, 0
	v_mov_b32_e32 v22, 0
	v_mov_b32_e32 v21, 0
	v_mov_b32_e32 v20, 0
	v_mov_b32_e32 v67, 0
	v_mov_b32_e32 v66, 0
	v_mov_b32_e32 v65, 0
	v_mov_b32_e32 v64, 0
	v_mov_b32_e32 v63, 0
	v_mov_b32_e32 v62, 0
	v_mov_b32_e32 v61, 0
	v_mov_b32_e32 v60, 0
	v_mov_b32_e32 v59, 0
	v_mov_b32_e32 v58, 0
	v_mov_b32_e32 v57, 0
	v_mov_b32_e32 v56, 0
	v_mov_b32_e32 v55, 0
	v_mov_b32_e32 v54, 0
	v_mov_b32_e32 v53, 0
	v_mov_b32_e32 v52, 0
	v_mov_b32_e32 v51, 0
	v_mov_b32_e32 v50, 0
	v_mov_b32_e32 v49, 0
	v_mov_b32_e32 v48, 0
	v_mov_b32_e32 v47, 0
	v_mov_b32_e32 v46, 0
	v_mov_b32_e32 v45, 0
	v_mov_b32_e32 v44, 0
	v_mov_b32_e32 v43, 0
	v_mov_b32_e32 v42, 0
	v_mov_b32_e32 v41, 0
	v_mov_b32_e32 v40, 0
	v_mov_b32_e32 v39, 0
	v_mov_b32_e32 v38, 0
	v_mov_b32_e32 v37, 0
	v_mov_b32_e32 v36, 0
	s_waitcnt vmcnt(2)
	v_mov_b32_e32 v84, 0
	s_cbranch_vccz .LBB0_678
	s_mul_i32 s1, s72, 0x1a00
	s_mul_hi_u32 s0, s72, 0x1a00
	s_add_u32 s1, s21, s1
	s_addc_u32 s10, s22, s0
	s_lshl_b32 s0, s14, 1
	v_lshl_or_b32 v4, s12, 5, v116
	s_add_u32 s0, s1, s0
	v_mul_u32_u24_e32 v4, 0xd00, v4
	s_addc_u32 s1, s10, 0
	v_lshlrev_b32_e32 v196, 1, v4
	v_lshl_add_u64 v[4:5], s[0:1], 0, v[196:197]
	s_lshl_b32 s0, s13, 7
	s_mov_b32 s1, s73
	v_lshl_add_u64 v[4:5], v[4:5], 0, s[0:1]
	v_lshlrev_b32_e32 v196, 4, v3
	v_lshl_add_u64 v[4:5], v[4:5], 0, v[196:197]
	s_mov_b64 s[10:11], 0xce00e00
	s_mov_b32 s1, 0xce00000
	v_lshl_add_u64 v[6:7], v[4:5], 0, s[10:11]
	v_add_co_u32_e32 v4, vcc, s1, v4
	s_mul_i32 s1, s19, 0x600
	s_nop 0
	v_addc_co_u32_e32 v5, vcc, 0, v5, vcc
	global_load_dwordx4 v[100:103], v[6:7], off offset:32
	global_load_dwordx4 v[104:107], v[6:7], off offset:64
	global_load_dwordx4 v[108:111], v[4:5], off offset:3584
	global_load_dwordx4 v[112:115], v[6:7], off offset:96
	v_lshlrev_b32_e32 v4, 3, v118
	v_lshlrev_b32_e32 v6, 4, v118
	v_and_b32_e32 v5, 24, v4
	v_and_b32_e32 v6, 0xc0, v6
	v_lshlrev_b32_e32 v7, 1, v118
	v_and_b32_e32 v7, 32, v7
	v_and_b32_e32 v4, 0x100, v4
	v_add3_u32 v5, 0, v5, v6
	v_add3_u32 v119, v5, v7, v4
	v_lshlrev_b32_e32 v5, 4, v116
	v_and_b32_e32 v5, 0x70, v5
	v_or_b32_e32 v4, s0, v196
	v_bitop3_b32 v121, s0, v5, v196 bitop3:0x36
	s_movk_i32 s0, 0x60
	v_bitop3_b32 v122, v4, v5, 32 bitop3:0x36
	v_bitop3_b32 v123, v4, v5, 64 bitop3:0x36
	s_waitcnt vmcnt(5)
	v_bitop3_b32 v124, v4, v5, s0 bitop3:0x36
	v_or_b32_e32 v4, s1, v196
	v_sub_u32_e32 v4, v4, v117
	s_lshl_b32 s0, s12, 7
	s_waitcnt lgkmcnt(0)
	s_barrier
	v_subrev_u32_e32 v4, s0, v4
	v_mov_b32_e32 v36, v197
	v_mov_b32_e32 v37, v197
	v_mov_b32_e32 v50, v197
	v_mov_b32_e32 v51, v197
	v_add_u32_e32 v126, 0, v4
	v_mov_b32_e32 v38, v197
	v_mov_b32_e32 v39, v197
	v_mov_b32_e32 v40, v197
	v_mov_b32_e32 v41, v197
	v_mov_b32_e32 v42, v197
	v_mov_b32_e32 v43, v197
	v_mov_b32_e32 v44, v197
	v_mov_b32_e32 v45, v197
	v_mov_b32_e32 v46, v197
	v_mov_b32_e32 v47, v197
	v_mov_b32_e32 v48, v197
	v_mov_b32_e32 v49, v197
	v_mov_b64_e32 v[66:67], v[50:51]
	v_mov_b64_e32 v[20:21], v[36:37]
	v_mov_b64_e32 v[4:5], v[36:37]
	s_mov_b32 s19, 0
	v_lshl_add_u32 v120, v116, 8, 0
	v_add_u32_e32 v125, s20, v117
	v_mov_b32_e32 v127, 0xf149f2ca
	s_waitcnt vmcnt(4)
	v_mov_b32_e32 v128, 0
	s_movk_i32 s21, 0xbf00
	v_mov_b64_e32 v[64:65], v[48:49]
	v_mov_b64_e32 v[62:63], v[46:47]
	v_mov_b64_e32 v[60:61], v[44:45]
	v_mov_b64_e32 v[58:59], v[42:43]
	v_mov_b64_e32 v[56:57], v[40:41]
	v_mov_b64_e32 v[54:55], v[38:39]
	v_mov_b64_e32 v[52:53], v[36:37]
	v_mov_b64_e32 v[22:23], v[38:39]
	v_mov_b64_e32 v[24:25], v[40:41]
	v_mov_b64_e32 v[26:27], v[42:43]
	v_mov_b64_e32 v[28:29], v[44:45]
	v_mov_b64_e32 v[30:31], v[46:47]
	v_mov_b64_e32 v[32:33], v[48:49]
	v_mov_b64_e32 v[34:35], v[50:51]
	v_mov_b64_e32 v[6:7], v[38:39]
	v_mov_b64_e32 v[8:9], v[40:41]
	v_mov_b64_e32 v[10:11], v[42:43]
	v_mov_b64_e32 v[12:13], v[44:45]
	v_mov_b64_e32 v[14:15], v[46:47]
	v_mov_b64_e32 v[16:17], v[48:49]
	v_mov_b64_e32 v[18:19], v[50:51]
	s_mov_b32 s22, 0
	s_setprio 1

; #define LAS __attribute__((address_space(3)))
; __device__ __forceinline__ int crow(int r, int hi) { return (r & 3) + 8 * (r >> 2) + 4 * hi; }
; #define BARRIER1() asm volatile("s_waitcnt lgkmcnt(0)\n\ts_barrier" ::: "memory")
; __device__ __forceinline__ int crow(int r, int hi) { return (r & 3) + 8 * (r >> 2) + 4 * hi; }
; __device__ __forceinline__ int crow(int r, int hi) { return (r & 3) + 8 * (r >> 2) + 4 * hi; }
; __device__ __forceinline__ void attn_unit_sample(LAS unsigned char* lds, const float* Kg, const float* Vg, const float* Kl, const float* Vl, const bf16* Qrow0, bf16* Orow0,
;                                                  int qpos0, int h, const float* gnorm) {
;     ...
;       BARRIER1(); }
;   }
;     ...
;   __syncthreads();
;   if (hi == 0) li_l[r32] = l_reg;
;   asm volatile("s_waitcnt lgkmcnt(0)" ::: "memory");
;   float rli[16];
; #pragma unroll
;   for (int r = 0; r < 16; ++r) rli[r] = __builtin_amdgcn_rcpf(li_l[crow(r, hi)]);
;   LAS float* X = (LAS float*)lds + rb * 4096 + lane;
;   if (live && g == 1) {
; #pragma unroll
;     for (int r = 0; r < 16; ++r)
; #pragma unroll
;       for (int d0 = 0; d0 < 4; ++d0) X[(r * 4 + d0) * 64] = o[d0][r] * rli[r];
;   }
.LBB0_678:
	s_setprio 0
	v_cmp_gt_u32_e32 vcc, 32, v118
	s_waitcnt lgkmcnt(0)
	s_barrier
	s_and_saveexec_b64 s[0:1], vcc
	v_lshl_add_u32 v68, v116, 2, s20
	ds_write_b32 v68, v84
	s_or_b64 exec, exec, s[0:1]
	s_waitcnt lgkmcnt(0)
	v_lshl_add_u32 v68, v3, 4, s20
	ds_read_b128 v[72:75], v68
	ds_read_b128 v[80:83], v68 offset:32
	ds_read_b128 v[84:87], v68 offset:64
	s_waitcnt vmcnt(0)
	ds_read_b128 v[90:93], v68 offset:96
	s_lshl_b32 s0, s12, 14
	s_add_i32 s0, s0, 0
	s_waitcnt lgkmcnt(3)
	v_rcp_f32_e32 v71, v72
	v_rcp_f32_e32 v72, v73
	v_rcp_f32_e32 v89, v74
	v_rcp_f32_e32 v78, v75
	s_waitcnt lgkmcnt(2)
	v_rcp_f32_e32 v77, v80
	v_rcp_f32_e32 v80, v81
	v_rcp_f32_e32 v79, v82
	v_rcp_f32_e32 v82, v83
	s_waitcnt lgkmcnt(1)
	v_rcp_f32_e32 v81, v84
	v_rcp_f32_e32 v84, v85
	v_rcp_f32_e32 v83, v86
	v_rcp_f32_e32 v87, v87
	s_waitcnt lgkmcnt(0)
	v_rcp_f32_e32 v88, v90
	v_rcp_f32_e32 v86, v91
	v_rcp_f32_e32 v85, v92
	v_rcp_f32_e32 v73, v93
	s_cmp_eq_u32 s13, 0
	v_lshl_add_u32 v76, v118, 2, s0
	s_cselect_b64 s[6:7], -1, 0
	s_xor_b64 s[0:1], s[8:9], -1
	s_or_b64 s[6:7], s[0:1], s[6:7]
	s_and_b64 vcc, exec, s[6:7]
	s_cbranch_vccnz .LBB0_682
	v_mul_f32_e32 v68, v36, v71
	v_mul_f32_e32 v69, v52, v71
	ds_write2st64_b32 v76, v68, v69 offset1:1
	v_mul_f32_e32 v68, v20, v71
	v_mul_f32_e32 v69, v4, v71
	ds_write2st64_b32 v76, v68, v69 offset0:2 offset1:3
	v_mul_f32_e32 v68, v37, v72
	v_mul_f32_e32 v69, v53, v72
	ds_write2st64_b32 v76, v68, v69 offset0:4 offset1:5
	v_mul_f32_e32 v68, v21, v72
	v_mul_f32_e32 v69, v5, v72
	ds_write2st64_b32 v76, v68, v69 offset0:6 offset1:7
	v_mul_f32_e32 v68, v38, v89
	v_mul_f32_e32 v69, v54, v89
	ds_write2st64_b32 v76, v68, v69 offset0:8 offset1:9
	v_mul_f32_e32 v68, v22, v89
	v_mul_f32_e32 v69, v6, v89
	ds_write2st64_b32 v76, v68, v69 offset0:10 offset1:11
	v_mul_f32_e32 v68, v39, v78
	v_mul_f32_e32 v69, v55, v78
	ds_write2st64_b32 v76, v68, v69 offset0:12 offset1:13
	v_mul_f32_e32 v68, v23, v78
	v_mul_f32_e32 v69, v7, v78
	ds_write2st64_b32 v76, v68, v69 offset0:14 offset1:15
	v_mul_f32_e32 v68, v40, v77
	v_mul_f32_e32 v69, v56, v77
	ds_write2st64_b32 v76, v68, v69 offset0:16 offset1:17
	v_mul_f32_e32 v68, v24, v77
	v_mul_f32_e32 v69, v8, v77
	ds_write2st64_b32 v76, v68, v69 offset0:18 offset1:19
	v_mul_f32_e32 v68, v41, v80
	v_mul_f32_e32 v69, v57, v80
	ds_write2st64_b32 v76, v68, v69 offset0:20 offset1:21
	v_mul_f32_e32 v68, v25, v80
	v_mul_f32_e32 v69, v9, v80
	ds_write2st64_b32 v76, v68, v69 offset0:22 offset1:23
	v_mul_f32_e32 v68, v42, v79
	v_mul_f32_e32 v69, v58, v79
	ds_write2st64_b32 v76, v68, v69 offset0:24 offset1:25
	v_mul_f32_e32 v68, v26, v79
	v_mul_f32_e32 v69, v10, v79
	ds_write2st64_b32 v76, v68, v69 offset0:26 offset1:27
	v_mul_f32_e32 v68, v43, v82
	v_mul_f32_e32 v69, v59, v82
	ds_write2st64_b32 v76, v68, v69 offset0:28 offset1:29
	v_mul_f32_e32 v68, v27, v82
	v_mul_f32_e32 v69, v11, v82
	ds_write2st64_b32 v76, v68, v69 offset0:30 offset1:31
	v_mul_f32_e32 v68, v44, v81
	v_mul_f32_e32 v69, v60, v81
	ds_write2st64_b32 v76, v68, v69 offset0:32 offset1:33
	v_mul_f32_e32 v68, v28, v81
	v_mul_f32_e32 v69, v12, v81
	ds_write2st64_b32 v76, v68, v69 offset0:34 offset1:35
	v_mul_f32_e32 v68, v45, v84
	v_mul_f32_e32 v69, v61, v84
	ds_write2st64_b32 v76, v68, v69 offset0:36 offset1:37
	v_mul_f32_e32 v68, v29, v84
	v_mul_f32_e32 v69, v13, v84
	ds_write2st64_b32 v76, v68, v69 offset0:38 offset1:39
	v_mul_f32_e32 v68, v46, v83
	v_mul_f32_e32 v69, v62, v83
	ds_write2st64_b32 v76, v68, v69 offset0:40 offset1:41
	v_mul_f32_e32 v68, v30, v83
	v_mul_f32_e32 v69, v14, v83
	ds_write2st64_b32 v76, v68, v69 offset0:42 offset1:43
	v_mul_f32_e32 v68, v47, v87
	v_mul_f32_e32 v69, v63, v87
	ds_write2st64_b32 v76, v68, v69 offset0:44 offset1:45
	v_mul_f32_e32 v68, v31, v87
	v_mul_f32_e32 v69, v15, v87
	ds_write2st64_b32 v76, v68, v69 offset0:46 offset1:47
	v_mul_f32_e32 v68, v48, v88
	v_mul_f32_e32 v69, v64, v88
	ds_write2st64_b32 v76, v68, v69 offset0:48 offset1:49
	v_mul_f32_e32 v68, v32, v88
	v_mul_f32_e32 v69, v16, v88
	ds_write2st64_b32 v76, v68, v69 offset0:50 offset1:51
	v_mul_f32_e32 v68, v49, v86
	v_mul_f32_e32 v69, v65, v86
	ds_write2st64_b32 v76, v68, v69 offset0:52 offset1:53
	v_mul_f32_e32 v68, v33, v86
	v_mul_f32_e32 v69, v17, v86
	ds_write2st64_b32 v76, v68, v69 offset0:54 offset1:55
	v_mul_f32_e32 v68, v50, v85
	v_mul_f32_e32 v69, v66, v85
	ds_write2st64_b32 v76, v68, v69 offset0:56 offset1:57
	v_mul_f32_e32 v68, v34, v85
	v_mul_f32_e32 v69, v18, v85
	ds_write2st64_b32 v76, v68, v69 offset0:58 offset1:59
	v_mul_f32_e32 v68, v51, v73
	v_mul_f32_e32 v69, v67, v73
	ds_write2st64_b32 v76, v68, v69 offset0:60 offset1:61
	v_mul_f32_e32 v68, v35, v73
	v_mul_f32_e32 v69, v19, v73
	ds_write2st64_b32 v76, v68, v69 offset0:62 offset1:63

; #define PG8_STAGE(bufoff, gbase, voff) do { _Pragma("unroll") for (int _i = 0; _i < 2; ++_i) \
;         __builtin_amdgcn_global_load_lds((const unsigned*)((const char*)(gbase) + (voff)[_i]), (PG8_LAS unsigned*)(lds + (bufoff) + ldsw + _i * 8192), 16, 0, 0); } while (0)
; #define PG8_LDA(dst, b, h) do { _Pragma("unroll") for (int m = 0; m < 4; ++m) _Pragma("unroll") for (int k = 0; k < 2; ++k) dst[m][k] = *(const PG8_LAS bf16x8*)(lds + PG8_SA(b, h) + aoff + m * 2048 + k * 1024); } while (0)
; #define PG8_LDB(dst, b, h) do { _Pragma("unroll") for (int n = 0; n < 2; ++n) _Pragma("unroll") for (int k = 0; k < 2; ++k) dst[n][k] = *(const PG8_LAS bf16x8*)(lds + PG8_SB(b, h) + boff + n * 2048 + k * 1024); } while (0)
; #define PG8_MMA(ai, bj, At, Bt) do { __builtin_amdgcn_s_setprio(1); _Pragma("unroll") for (int m = 0; m < 4; ++m) _Pragma("unroll") for (int n = 0; n < 2; ++n) _Pragma("unroll") for (int k = 0; k < 2; ++k) \
;         acc[ai][bj][m][n] = __builtin_amdgcn_mfma_f32_16x16x32_bf16(Bt[n][k], At[m][k], acc[ai][bj][m][n], 0, 0, 0); __builtin_amdgcn_s_setprio(0); } while (0)
; #define PG8_WAIT_V(n) asm volatile("s_waitcnt vmcnt(" #n ")" ::: "memory")
; #define PG8_WAIT_L(n) asm volatile("s_waitcnt lgkmcnt(" #n ")" ::: "memory")
; template <class Epi, class Sched, bool ALIGN_EPI = false, bool SP2 = false>
; __device__ __forceinline__ void gemm_phase(PG8_LAS unsigned char* lds, const Gemm g, const Sched& S, const Epi& E) {
;     ...
;             const bool last = (t == nt - 2);
;             const char* a1 = cA + (size_t)(t + 1) * kstep;
;             const char* a2 = last ? nA : cA + (size_t)(t + 2) * kstep; const char* b2 = last ? nB : cB + (size_t)(t + 2) * kstep;
;             const char* a3 = a2 + kstep; const char* b3 = b2 + kstep;
;             if (last && has_next) S.a_ready(nxt);
;             if constexpr (SP2) {
;             PG8_LDB(B0, 0, 0); PG8_LDB(B1, 0, 1); PG8_SCHED; PG8_LDA(At, 0, 0); PG8_STAGE(PG8_SA(1, 1), a1 + hstep, voffA);
;             PG8_WAIT_V(8); PG8_WAIT_L(0); PG8_BAR; PG8_MMA(0, 0, At, B0); PG8_MMA(0, 1, At, B1); PG8_BAR; PG8_SCHED;
;             PG8_LDA(At, 0, 1); PG8_STAGE(PG8_SB(0, 0), b2, voffB); PG8_STAGE(PG8_SB(0, 1), b2 + hstep, voffB); PG8_STAGE(PG8_SA(0, 0), a2, voffA);
;             PG8_WAIT_V(8); PG8_WAIT_L(0); PG8_BAR; PG8_MMA(1, 0, At, B0); PG8_MMA(1, 1, At, B1); PG8_BAR; PG8_SCHED;
.LBB0_831:
	s_add_u32 s28, s26, 0xfffc0080
	s_addc_u32 s29, s27, -1
	s_add_i32 s66, 0, 0x10000
	s_cmp_eq_u32 s92, 12
	s_cselect_b32 s31, s21, s29
	s_cselect_b32 s30, s64, s28
	s_cselect_b32 s29, s19, s89
	s_cselect_b32 s28, s65, s72
	s_add_i32 s93, 0, 0x14000
	v_add_u32_e32 v136, s66, v226
	v_add_u32_e32 v160, s93, v226
	ds_read_b128 v[116:119], v136
	ds_read_b128 v[120:123], v136 offset:1024
	ds_read_b128 v[132:135], v136 offset:2048
	ds_read_b128 v[136:139], v136 offset:3072
	ds_read_b128 v[144:147], v160
	ds_read_b128 v[152:155], v160 offset:1024
	ds_read_b128 v[156:159], v160 offset:2048
	ds_read_b128 v[160:163], v160 offset:3072
	v_lshl_add_u64 v[220:221], s[26:27], 0, v[216:217]
	s_add_i32 m0, s45, 0xc000
	ds_read_b128 v[164:167], v228
	ds_read_b128 v[168:171], v228 offset:1024
	ds_read_b128 v[172:175], v228 offset:2048
	ds_read_b128 v[176:179], v228 offset:3072
	ds_read_b128 v[180:183], v228 offset:4096
	ds_read_b128 v[184:187], v228 offset:5120
	ds_read_b128 v[188:191], v228 offset:6144
	ds_read_b128 v[192:195], v228 offset:7168
	global_load_lds_dwordx4 v[220:221], off
	v_lshl_add_u64 v[220:221], s[26:27], 0, v[218:219]
	s_add_i32 m0, s45, 0xe000
	s_nop 0
	global_load_lds_dwordx4 v[220:221], off
	s_waitcnt vmcnt(8)
	s_waitcnt lgkmcnt(0)
	s_barrier
	s_setprio 1
	s_waitcnt lgkmcnt(0)
	v_mfma_f32_16x16x32_bf16 v[148:151], v[116:119], v[164:167], v[148:151]
	v_mfma_f32_16x16x32_bf16 v[140:143], v[132:135], v[164:167], v[140:143]
	v_mfma_f32_16x16x32_bf16 v[112:115], v[116:119], v[172:175], v[112:115]
	v_mfma_f32_16x16x32_bf16 v[108:111], v[132:135], v[172:175], v[108:111]
	v_mfma_f32_16x16x32_bf16 v[96:99], v[116:119], v[180:183], v[96:99]
	v_mfma_f32_16x16x32_bf16 v[92:95], v[132:135], v[180:183], v[92:95]
	v_mfma_f32_16x16x32_bf16 v[80:83], v[116:119], v[188:191], v[80:83]
	v_mfma_f32_16x16x32_bf16 v[76:79], v[132:135], v[188:191], v[76:79]
	v_mfma_f32_16x16x32_bf16 v[148:151], v[120:123], v[168:171], v[148:151]
	v_mfma_f32_16x16x32_bf16 v[140:143], v[136:139], v[168:171], v[140:143]
	v_mfma_f32_16x16x32_bf16 v[112:115], v[120:123], v[176:179], v[112:115]
	v_mfma_f32_16x16x32_bf16 v[108:111], v[136:139], v[176:179], v[108:111]
	v_mfma_f32_16x16x32_bf16 v[96:99], v[120:123], v[184:187], v[96:99]
	v_mfma_f32_16x16x32_bf16 v[92:95], v[136:139], v[184:187], v[92:95]
	v_mfma_f32_16x16x32_bf16 v[80:83], v[120:123], v[192:195], v[80:83]
	v_mfma_f32_16x16x32_bf16 v[76:79], v[136:139], v[192:195], v[76:79]
	s_setprio 0
	s_setprio 1
	v_mfma_f32_16x16x32_bf16 v[128:131], v[144:147], v[164:167], v[128:131]
	v_mfma_f32_16x16x32_bf16 v[124:127], v[156:159], v[164:167], v[124:127]
	v_mfma_f32_16x16x32_bf16 v[104:107], v[144:147], v[172:175], v[104:107]
	v_mfma_f32_16x16x32_bf16 v[100:103], v[156:159], v[172:175], v[100:103]
	v_mfma_f32_16x16x32_bf16 v[88:91], v[144:147], v[180:183], v[88:91]
	v_mfma_f32_16x16x32_bf16 v[84:87], v[156:159], v[180:183], v[84:87]
	v_mfma_f32_16x16x32_bf16 v[72:75], v[144:147], v[188:191], v[72:75]
	v_mfma_f32_16x16x32_bf16 v[68:71], v[156:159], v[188:191], v[68:71]
	v_mfma_f32_16x16x32_bf16 v[128:131], v[152:155], v[168:171], v[128:131]
	v_mfma_f32_16x16x32_bf16 v[124:127], v[160:163], v[168:171], v[124:127]
	v_mfma_f32_16x16x32_bf16 v[104:107], v[152:155], v[176:179], v[104:107]
	v_mfma_f32_16x16x32_bf16 v[100:103], v[160:163], v[176:179], v[100:103]
	v_mfma_f32_16x16x32_bf16 v[88:91], v[152:155], v[184:187], v[88:91]
	v_mfma_f32_16x16x32_bf16 v[84:87], v[160:163], v[184:187], v[84:87]
	v_mfma_f32_16x16x32_bf16 v[72:75], v[152:155], v[192:195], v[72:75]
	v_mfma_f32_16x16x32_bf16 v[68:71], v[160:163], v[192:195], v[68:71]
	s_setprio 0
	s_barrier
	s_add_i32 s66, s66, s44
	v_lshl_add_u64 v[220:221], s[28:29], 0, v[196:197]
	s_mov_b32 m0, s66
	ds_read_b128 v[164:167], v228 offset:16384
	ds_read_b128 v[168:171], v228 offset:17408
	ds_read_b128 v[172:175], v228 offset:18432
	ds_read_b128 v[176:179], v228 offset:19456
	ds_read_b128 v[180:183], v228 offset:20480
	ds_read_b128 v[184:187], v228 offset:21504
	ds_read_b128 v[188:191], v228 offset:22528
	ds_read_b128 v[192:195], v228 offset:23552
	global_load_lds_dwordx4 v[220:221], off
	s_add_i32 m0, s66, 0x2000
	s_add_u32 s66, s28, 0x40000
	v_lshl_add_u64 v[222:223], s[28:29], 0, v[210:211]
	s_addc_u32 s67, s29, 0
	s_add_i32 s93, s93, s44
	global_load_lds_dwordx4 v[222:223], off
	v_lshl_add_u64 v[224:225], s[66:67], 0, v[196:197]
	s_mov_b32 m0, s93
	v_lshl_add_u64 v[246:247], s[30:31], 0, v[212:213]
	global_load_lds_dwordx4 v[224:225], off
	v_lshl_add_u64 v[224:225], s[66:67], 0, v[210:211]
	s_add_i32 m0, s93, 0x2000
	s_nop 0
	global_load_lds_dwordx4 v[224:225], off
	v_lshl_add_u64 v[224:225], s[30:31], 0, v[214:215]
	s_mov_b32 m0, s45
	s_nop 0
	global_load_lds_dwordx4 v[224:225], off
	s_mov_b32 m0, s48
	s_nop 0
	global_load_lds_dwordx4 v[246:247], off
	s_waitcnt vmcnt(8)
	s_waitcnt lgkmcnt(0)
	s_barrier
; #define PG8_STAGE(bufoff, gbase, voff) do { _Pragma("unroll") for (int _i = 0; _i < 2; ++_i) \
;         __builtin_amdgcn_global_load_lds((const unsigned*)((const char*)(gbase) + (voff)[_i]), (PG8_LAS unsigned*)(lds + (bufoff) + ldsw + _i * 8192), 16, 0, 0); } while (0)
; #define PG8_LDA(dst, b, h) do { _Pragma("unroll") for (int m = 0; m < 4; ++m) _Pragma("unroll") for (int k = 0; k < 2; ++k) dst[m][k] = *(const PG8_LAS bf16x8*)(lds + PG8_SA(b, h) + aoff + m * 2048 + k * 1024); } while (0)
; #define PG8_LDB(dst, b, h) do { _Pragma("unroll") for (int n = 0; n < 2; ++n) _Pragma("unroll") for (int k = 0; k < 2; ++k) dst[n][k] = *(const PG8_LAS bf16x8*)(lds + PG8_SB(b, h) + boff + n * 2048 + k * 1024); } while (0)
; #define PG8_MMA(ai, bj, At, Bt) do { __builtin_amdgcn_s_setprio(1); _Pragma("unroll") for (int m = 0; m < 4; ++m) _Pragma("unroll") for (int n = 0; n < 2; ++n) _Pragma("unroll") for (int k = 0; k < 2; ++k) \
;         acc[ai][bj][m][n] = __builtin_amdgcn_mfma_f32_16x16x32_bf16(Bt[n][k], At[m][k], acc[ai][bj][m][n], 0, 0, 0); __builtin_amdgcn_s_setprio(0); } while (0)
; #define PG8_WAIT_V(n) asm volatile("s_waitcnt vmcnt(" #n ")" ::: "memory")
; #define PG8_WAIT_L(n) asm volatile("s_waitcnt lgkmcnt(" #n ")" ::: "memory")
; #define PG8_BAR __builtin_amdgcn_s_barrier()
; #define PG8_SCHED __builtin_amdgcn_sched_barrier(0)
; template <class Epi, class Sched, bool ALIGN_EPI = false, bool SP2 = false>
; __device__ __forceinline__ void gemm_phase(PG8_LAS unsigned char* lds, const Gemm g, const Sched& S, const Epi& E) {
;     ...
;             PG8_WAIT_V(8); PG8_WAIT_L(0); PG8_BAR; PG8_MMA(1, 0, At, B0); PG8_MMA(1, 1, At, B1); PG8_BAR; PG8_SCHED;
;             PG8_LDB(B0, 1, 0); PG8_LDB(B1, 1, 1); PG8_SCHED; PG8_LDA(At, 1, 0); PG8_STAGE(PG8_SA(0, 1), a2 + hstep, voffA);
;             PG8_WAIT_V(8); PG8_WAIT_L(0); PG8_BAR; PG8_MMA(0, 0, At, B0); PG8_MMA(0, 1, At, B1); PG8_BAR; PG8_SCHED;
	s_setprio 1
	s_waitcnt lgkmcnt(0)
	v_mfma_f32_16x16x32_bf16 v[64:67], v[116:119], v[164:167], v[64:67]
	v_mfma_f32_16x16x32_bf16 v[60:63], v[132:135], v[164:167], v[60:63]
	v_mfma_f32_16x16x32_bf16 v[48:51], v[116:119], v[172:175], v[48:51]
	v_mfma_f32_16x16x32_bf16 v[44:47], v[132:135], v[172:175], v[44:47]
	v_mfma_f32_16x16x32_bf16 v[32:35], v[116:119], v[180:183], v[32:35]
	v_mfma_f32_16x16x32_bf16 v[28:31], v[132:135], v[180:183], v[28:31]
	v_mfma_f32_16x16x32_bf16 v[16:19], v[116:119], v[188:191], v[16:19]
	v_mfma_f32_16x16x32_bf16 v[12:15], v[132:135], v[188:191], v[12:15]
	v_mfma_f32_16x16x32_bf16 v[64:67], v[120:123], v[168:171], v[64:67]
	v_mfma_f32_16x16x32_bf16 v[60:63], v[136:139], v[168:171], v[60:63]
	v_mfma_f32_16x16x32_bf16 v[48:51], v[120:123], v[176:179], v[48:51]
	v_mfma_f32_16x16x32_bf16 v[44:47], v[136:139], v[176:179], v[44:47]
	v_mfma_f32_16x16x32_bf16 v[32:35], v[120:123], v[184:187], v[32:35]
	v_mfma_f32_16x16x32_bf16 v[28:31], v[136:139], v[184:187], v[28:31]
	v_mfma_f32_16x16x32_bf16 v[16:19], v[120:123], v[192:195], v[16:19]
	v_mfma_f32_16x16x32_bf16 v[12:15], v[136:139], v[192:195], v[12:15]
	s_setprio 0
	s_setprio 1
	v_mfma_f32_16x16x32_bf16 v[56:59], v[144:147], v[164:167], v[56:59]
	v_mfma_f32_16x16x32_bf16 v[52:55], v[156:159], v[164:167], v[52:55]
	v_mfma_f32_16x16x32_bf16 v[40:43], v[144:147], v[172:175], v[40:43]
	v_mfma_f32_16x16x32_bf16 v[36:39], v[156:159], v[172:175], v[36:39]
	v_mfma_f32_16x16x32_bf16 v[24:27], v[144:147], v[180:183], v[24:27]
	v_mfma_f32_16x16x32_bf16 v[20:23], v[156:159], v[180:183], v[20:23]
	v_mfma_f32_16x16x32_bf16 v[8:11], v[144:147], v[188:191], v[8:11]
	v_mfma_f32_16x16x32_bf16 v[4:7], v[156:159], v[188:191], v[4:7]
	v_mfma_f32_16x16x32_bf16 v[56:59], v[152:155], v[168:171], v[56:59]
	v_mfma_f32_16x16x32_bf16 v[52:55], v[160:163], v[168:171], v[52:55]
	v_mfma_f32_16x16x32_bf16 v[40:43], v[152:155], v[176:179], v[40:43]
	v_mfma_f32_16x16x32_bf16 v[36:39], v[160:163], v[176:179], v[36:39]
	v_mfma_f32_16x16x32_bf16 v[24:27], v[152:155], v[184:187], v[24:27]
	v_mfma_f32_16x16x32_bf16 v[20:23], v[160:163], v[184:187], v[20:23]
	v_mfma_f32_16x16x32_bf16 v[8:11], v[152:155], v[192:195], v[8:11]
	v_mfma_f32_16x16x32_bf16 v[4:7], v[160:163], v[192:195], v[4:7]
	s_setprio 0
	s_barrier
	s_add_i32 s66, 0, 0x18000
	s_add_i32 s67, 0, 0x1c000
	v_add_u32_e32 v136, s66, v226
	v_add_u32_e32 v160, s67, v226
	ds_read_b128 v[116:119], v136
	ds_read_b128 v[120:123], v136 offset:1024
	ds_read_b128 v[132:135], v136 offset:2048
	ds_read_b128 v[136:139], v136 offset:3072
	ds_read_b128 v[144:147], v160
	ds_read_b128 v[152:155], v160 offset:1024
	ds_read_b128 v[156:159], v160 offset:2048
	ds_read_b128 v[160:163], v160 offset:3072
	s_add_u32 s30, s30, 0x40000
	s_addc_u32 s31, s31, 0
	s_mov_b32 m0, s49
	v_lshl_add_u64 v[248:249], s[30:31], 0, v[214:215]
	ds_read_b128 v[164:167], v228 offset:32768
	ds_read_b128 v[168:171], v228 offset:33792
	ds_read_b128 v[172:175], v228 offset:34816
	ds_read_b128 v[176:179], v228 offset:35840
	ds_read_b128 v[180:183], v228 offset:36864
	ds_read_b128 v[184:187], v228 offset:37888
	ds_read_b128 v[188:191], v228 offset:38912
	ds_read_b128 v[192:195], v228 offset:39936
	global_load_lds_dwordx4 v[248:249], off
	v_lshl_add_u64 v[248:249], s[30:31], 0, v[212:213]
	s_mov_b32 m0, s52
	s_nop 0
	global_load_lds_dwordx4 v[248:249], off
	s_waitcnt vmcnt(8)
	s_waitcnt lgkmcnt(0)
	s_barrier
	s_setprio 1
	s_waitcnt lgkmcnt(0)
	v_mfma_f32_16x16x32_bf16 v[148:151], v[116:119], v[164:167], v[148:151]
	v_mfma_f32_16x16x32_bf16 v[140:143], v[132:135], v[164:167], v[140:143]
	v_mfma_f32_16x16x32_bf16 v[112:115], v[116:119], v[172:175], v[112:115]
	v_mfma_f32_16x16x32_bf16 v[108:111], v[132:135], v[172:175], v[108:111]
	v_mfma_f32_16x16x32_bf16 v[96:99], v[116:119], v[180:183], v[96:99]
	v_mfma_f32_16x16x32_bf16 v[92:95], v[132:135], v[180:183], v[92:95]
	v_mfma_f32_16x16x32_bf16 v[80:83], v[116:119], v[188:191], v[80:83]
	v_mfma_f32_16x16x32_bf16 v[76:79], v[132:135], v[188:191], v[76:79]
	v_mfma_f32_16x16x32_bf16 v[148:151], v[120:123], v[168:171], v[148:151]
	v_mfma_f32_16x16x32_bf16 v[140:143], v[136:139], v[168:171], v[140:143]
	v_mfma_f32_16x16x32_bf16 v[112:115], v[120:123], v[176:179], v[112:115]
	v_mfma_f32_16x16x32_bf16 v[108:111], v[136:139], v[176:179], v[108:111]
	v_mfma_f32_16x16x32_bf16 v[96:99], v[120:123], v[184:187], v[96:99]
	v_mfma_f32_16x16x32_bf16 v[92:95], v[136:139], v[184:187], v[92:95]
	v_mfma_f32_16x16x32_bf16 v[80:83], v[120:123], v[192:195], v[80:83]
	v_mfma_f32_16x16x32_bf16 v[76:79], v[136:139], v[192:195], v[76:79]
	s_setprio 0
	s_setprio 1
	v_mfma_f32_16x16x32_bf16 v[128:131], v[144:147], v[164:167], v[128:131]
	v_mfma_f32_16x16x32_bf16 v[124:127], v[156:159], v[164:167], v[124:127]
	v_mfma_f32_16x16x32_bf16 v[104:107], v[144:147], v[172:175], v[104:107]
	v_mfma_f32_16x16x32_bf16 v[100:103], v[156:159], v[172:175], v[100:103]
	v_mfma_f32_16x16x32_bf16 v[88:91], v[144:147], v[180:183], v[88:91]
	v_mfma_f32_16x16x32_bf16 v[84:87], v[156:159], v[180:183], v[84:87]
	v_mfma_f32_16x16x32_bf16 v[72:75], v[144:147], v[188:191], v[72:75]
	v_mfma_f32_16x16x32_bf16 v[68:71], v[156:159], v[188:191], v[68:71]
	v_mfma_f32_16x16x32_bf16 v[128:131], v[152:155], v[168:171], v[128:131]
	v_mfma_f32_16x16x32_bf16 v[124:127], v[160:163], v[168:171], v[124:127]
	v_mfma_f32_16x16x32_bf16 v[104:107], v[152:155], v[176:179], v[104:107]
	v_mfma_f32_16x16x32_bf16 v[100:103], v[160:163], v[176:179], v[100:103]
	v_mfma_f32_16x16x32_bf16 v[88:91], v[152:155], v[184:187], v[88:91]
	v_mfma_f32_16x16x32_bf16 v[84:87], v[160:163], v[184:187], v[84:87]
	v_mfma_f32_16x16x32_bf16 v[72:75], v[152:155], v[192:195], v[72:75]
	v_mfma_f32_16x16x32_bf16 v[68:71], v[160:163], v[192:195], v[68:71]
	s_setprio 0
	s_barrier
; #define PG8_STAGE(bufoff, gbase, voff) do { _Pragma("unroll") for (int _i = 0; _i < 2; ++_i) \
;         __builtin_amdgcn_global_load_lds((const unsigned*)((const char*)(gbase) + (voff)[_i]), (PG8_LAS unsigned*)(lds + (bufoff) + ldsw + _i * 8192), 16, 0, 0); } while (0)
; #define PG8_LDA(dst, b, h) do { _Pragma("unroll") for (int m = 0; m < 4; ++m) _Pragma("unroll") for (int k = 0; k < 2; ++k) dst[m][k] = *(const PG8_LAS bf16x8*)(lds + PG8_SA(b, h) + aoff + m * 2048 + k * 1024); } while (0)
; #define PG8_MMA(ai, bj, At, Bt) do { __builtin_amdgcn_s_setprio(1); _Pragma("unroll") for (int m = 0; m < 4; ++m) _Pragma("unroll") for (int n = 0; n < 2; ++n) _Pragma("unroll") for (int k = 0; k < 2; ++k) \
;         acc[ai][bj][m][n] = __builtin_amdgcn_mfma_f32_16x16x32_bf16(Bt[n][k], At[m][k], acc[ai][bj][m][n], 0, 0, 0); __builtin_amdgcn_s_setprio(0); } while (0)
; #define PG8_WAIT_V(n) asm volatile("s_waitcnt vmcnt(" #n ")" ::: "memory")
; #define PG8_WAIT_L(n) asm volatile("s_waitcnt lgkmcnt(" #n ")" ::: "memory")
; #define PG8_BAR __builtin_amdgcn_s_barrier()
; #define PG8_SCHED __builtin_amdgcn_sched_barrier(0)
; template <class Epi, class Sched, bool ALIGN_EPI = false, bool SP2 = false>
; __device__ __forceinline__ void gemm_phase(PG8_LAS unsigned char* lds, const Gemm g, const Sched& S, const Epi& E) {
;     ...
;         for (int t = 0; t < nt; t += 2) {
;     ...
;             PG8_LDA(At, 1, 1); PG8_STAGE(PG8_SB(1, 0), b3, voffB); PG8_STAGE(PG8_SB(1, 1), b3 + hstep, voffB); PG8_STAGE(PG8_SA(1, 0), a3, voffA);
;             PG8_WAIT_V(8); PG8_WAIT_L(0); PG8_BAR; PG8_MMA(1, 0, At, B0); PG8_MMA(1, 1, At, B1); PG8_BAR; PG8_SCHED;
	s_add_i32 s30, s66, s44
	v_lshl_add_u64 v[220:221], v[220:221], 0, s[78:79]
	s_mov_b32 m0, s30
	ds_read_b128 v[164:167], v228 offset:49152
	ds_read_b128 v[168:171], v228 offset:50176
	ds_read_b128 v[172:175], v228 offset:51200
	ds_read_b128 v[176:179], v228 offset:52224
	ds_read_b128 v[180:183], v228 offset:53248
	ds_read_b128 v[184:187], v228 offset:54272
	ds_read_b128 v[188:191], v228 offset:55296
	ds_read_b128 v[192:195], v228 offset:56320
	global_load_lds_dwordx4 v[220:221], off
	s_add_i32 m0, s30, 0x2000
	s_add_u32 s28, s28, 0x40080
	v_lshl_add_u64 v[220:221], v[222:223], 0, s[78:79]
	s_addc_u32 s29, s29, 0
	s_add_i32 s30, s67, s44
	global_load_lds_dwordx4 v[220:221], off
	v_lshl_add_u64 v[220:221], s[28:29], 0, v[196:197]
	s_mov_b32 m0, s30
	s_nop 0
	global_load_lds_dwordx4 v[220:221], off
	v_lshl_add_u64 v[220:221], s[28:29], 0, v[210:211]
	s_add_i32 m0, s30, 0x2000
	s_nop 0
	global_load_lds_dwordx4 v[220:221], off
	v_lshl_add_u64 v[220:221], v[224:225], 0, s[78:79]
	s_mov_b32 m0, s84
	s_nop 0
	global_load_lds_dwordx4 v[220:221], off
	v_lshl_add_u64 v[220:221], v[246:247], 0, s[78:79]
	s_mov_b32 m0, s85
	s_nop 0
	global_load_lds_dwordx4 v[220:221], off
	s_waitcnt vmcnt(8)
	s_waitcnt lgkmcnt(0)
	s_barrier
	s_setprio 1
	s_waitcnt lgkmcnt(0)
	v_mfma_f32_16x16x32_bf16 v[64:67], v[116:119], v[164:167], v[64:67]
	v_mfma_f32_16x16x32_bf16 v[60:63], v[132:135], v[164:167], v[60:63]
	v_mfma_f32_16x16x32_bf16 v[48:51], v[116:119], v[172:175], v[48:51]
	v_mfma_f32_16x16x32_bf16 v[44:47], v[132:135], v[172:175], v[44:47]
	v_mfma_f32_16x16x32_bf16 v[32:35], v[116:119], v[180:183], v[32:35]
	v_mfma_f32_16x16x32_bf16 v[28:31], v[132:135], v[180:183], v[28:31]
	v_mfma_f32_16x16x32_bf16 v[16:19], v[116:119], v[188:191], v[16:19]
	v_mfma_f32_16x16x32_bf16 v[12:15], v[132:135], v[188:191], v[12:15]
	v_mfma_f32_16x16x32_bf16 v[64:67], v[120:123], v[168:171], v[64:67]
	v_mfma_f32_16x16x32_bf16 v[60:63], v[136:139], v[168:171], v[60:63]
	v_mfma_f32_16x16x32_bf16 v[48:51], v[120:123], v[176:179], v[48:51]
	v_mfma_f32_16x16x32_bf16 v[44:47], v[136:139], v[176:179], v[44:47]
	v_mfma_f32_16x16x32_bf16 v[32:35], v[120:123], v[184:187], v[32:35]
	v_mfma_f32_16x16x32_bf16 v[28:31], v[136:139], v[184:187], v[28:31]
	v_mfma_f32_16x16x32_bf16 v[16:19], v[120:123], v[192:195], v[16:19]
	v_mfma_f32_16x16x32_bf16 v[12:15], v[136:139], v[192:195], v[12:15]
	s_setprio 0
	s_setprio 1
	v_mfma_f32_16x16x32_bf16 v[56:59], v[144:147], v[164:167], v[56:59]
	v_mfma_f32_16x16x32_bf16 v[52:55], v[156:159], v[164:167], v[52:55]
	v_mfma_f32_16x16x32_bf16 v[40:43], v[144:147], v[172:175], v[40:43]
	v_mfma_f32_16x16x32_bf16 v[36:39], v[156:159], v[172:175], v[36:39]
	v_mfma_f32_16x16x32_bf16 v[24:27], v[144:147], v[180:183], v[24:27]
	v_mfma_f32_16x16x32_bf16 v[20:23], v[156:159], v[180:183], v[20:23]
	v_mfma_f32_16x16x32_bf16 v[8:11], v[144:147], v[188:191], v[8:11]
	v_mfma_f32_16x16x32_bf16 v[4:7], v[156:159], v[188:191], v[4:7]
	v_mfma_f32_16x16x32_bf16 v[56:59], v[152:155], v[168:171], v[56:59]
	v_mfma_f32_16x16x32_bf16 v[52:55], v[160:163], v[168:171], v[52:55]
	v_mfma_f32_16x16x32_bf16 v[40:43], v[152:155], v[176:179], v[40:43]
	v_mfma_f32_16x16x32_bf16 v[36:39], v[160:163], v[176:179], v[36:39]
	v_mfma_f32_16x16x32_bf16 v[24:27], v[152:155], v[184:187], v[24:27]
	v_mfma_f32_16x16x32_bf16 v[20:23], v[160:163], v[184:187], v[20:23]
	v_mfma_f32_16x16x32_bf16 v[8:11], v[152:155], v[192:195], v[8:11]
	v_mfma_f32_16x16x32_bf16 v[4:7], v[160:163], v[192:195], v[4:7]
	s_setprio 0
	s_add_i32 s92, s92, 2
	s_add_u32 s26, s26, 0x100
	s_addc_u32 s27, s27, 0
	s_add_u32 s72, s72, 0x100
	s_addc_u32 s89, s89, 0
	s_cmp_gt_u32 s92, 13
	s_barrier
	s_cbranch_scc0 .LBB0_831
	s_and_b64 vcc, exec, s[16:17]
	s_cbranch_vccz .LBB0_834
	s_barrier

; #define PG8_STAGE(bufoff, gbase, voff) do { _Pragma("unroll") for (int _i = 0; _i < 2; ++_i) \
;         __builtin_amdgcn_global_load_lds((const unsigned*)((const char*)(gbase) + (voff)[_i]), (PG8_LAS unsigned*)(lds + (bufoff) + ldsw + _i * 8192), 16, 0, 0); } while (0)
; #define PG8_LDA(dst, b, h) do { _Pragma("unroll") for (int m = 0; m < 4; ++m) _Pragma("unroll") for (int k = 0; k < 2; ++k) dst[m][k] = *(const PG8_LAS bf16x8*)(lds + PG8_SA(b, h) + aoff + m * 2048 + k * 1024); } while (0)
; #define PG8_LDB(dst, b, h) do { _Pragma("unroll") for (int n = 0; n < 2; ++n) _Pragma("unroll") for (int k = 0; k < 2; ++k) dst[n][k] = *(const PG8_LAS bf16x8*)(lds + PG8_SB(b, h) + boff + n * 2048 + k * 1024); } while (0)
; #define PG8_MMA(ai, bj, At, Bt) do { __builtin_amdgcn_s_setprio(1); _Pragma("unroll") for (int m = 0; m < 4; ++m) _Pragma("unroll") for (int n = 0; n < 2; ++n) _Pragma("unroll") for (int k = 0; k < 2; ++k) \
;         acc[ai][bj][m][n] = __builtin_amdgcn_mfma_f32_16x16x32_bf16(Bt[n][k], At[m][k], acc[ai][bj][m][n], 0, 0, 0); __builtin_amdgcn_s_setprio(0); } while (0)
; #define PG8_WAIT_V(n) asm volatile("s_waitcnt vmcnt(" #n ")" ::: "memory")
; #define PG8_WAIT_L(n) asm volatile("s_waitcnt lgkmcnt(" #n ")" ::: "memory")
; template <class Epi, class Sched, bool ALIGN_EPI = false, bool SP2 = false>
; __device__ __forceinline__ void gemm_phase(PG8_LAS unsigned char* lds, const Gemm g, const Sched& S, const Epi& E) {
;     ...
;             const bool last = (t == nt - 2);
;             const char* a1 = cA + (size_t)(t + 1) * kstep;
;             const char* a2 = last ? nA : cA + (size_t)(t + 2) * kstep; const char* b2 = last ? nB : cB + (size_t)(t + 2) * kstep;
;             const char* a3 = a2 + kstep; const char* b3 = b2 + kstep;
;             if (last && has_next) S.a_ready(nxt);
;             if constexpr (SP2) {
;             PG8_LDB(B0, 0, 0); PG8_LDB(B1, 0, 1); PG8_SCHED; PG8_LDA(At, 0, 0); PG8_STAGE(PG8_SA(1, 1), a1 + hstep, voffA);
;             PG8_WAIT_V(8); PG8_WAIT_L(0); PG8_BAR; PG8_MMA(0, 0, At, B0); PG8_MMA(0, 1, At, B1); PG8_BAR; PG8_SCHED;
;             PG8_LDA(At, 0, 1); PG8_STAGE(PG8_SB(0, 0), b2, voffB); PG8_STAGE(PG8_SB(0, 1), b2 + hstep, voffB); PG8_STAGE(PG8_SA(0, 0), a2, voffA);
;             PG8_WAIT_V(8); PG8_WAIT_L(0); PG8_BAR; PG8_MMA(1, 0, At, B0); PG8_MMA(1, 1, At, B1); PG8_BAR; PG8_SCHED;
.LBB0_931:
	s_add_u32 s20, s18, 0xfffc0080
	s_addc_u32 s21, s19, -1
	s_add_i32 s64, 0, 0x10000
	s_cmp_eq_u32 s55, 12
	s_cselect_b32 s23, s13, s21
	s_cselect_b32 s22, s49, s20
	v_add_u32_e32 v144, s64, v146
	s_cselect_b32 s21, s11, s54
	s_cselect_b32 s20, s52, s53
	s_add_i32 s66, 0, 0x14000
	ds_read_b128 v[150:153], v144
	ds_read_b128 v[154:157], v144 offset:1024
	ds_read_b128 v[158:161], v144 offset:2048
	ds_read_b128 v[162:165], v144 offset:3072
	v_add_u32_e32 v144, s66, v146
	ds_read_b128 v[166:169], v144
	ds_read_b128 v[170:173], v144 offset:1024
	ds_read_b128 v[174:177], v144 offset:2048
	ds_read_b128 v[178:181], v144 offset:3072
	v_lshl_add_u64 v[144:145], s[18:19], 0, v[140:141]
	s_add_i32 m0, s29, 0xc000
	ds_read_b128 v[182:185], v148
	ds_read_b128 v[186:189], v148 offset:1024
	ds_read_b128 v[190:193], v148 offset:2048
	ds_read_b128 v[210:213], v148 offset:3072
	ds_read_b128 v[214:217], v148 offset:4096
	ds_read_b128 v[218:221], v148 offset:5120
	ds_read_b128 v[222:225], v148 offset:6144
	ds_read_b128 v[226:229], v148 offset:7168
	global_load_lds_dwordx4 v[144:145], off
	v_lshl_add_u64 v[144:145], s[18:19], 0, v[142:143]
	s_add_i32 m0, s29, 0xe000
	s_nop 0
	global_load_lds_dwordx4 v[144:145], off
	s_waitcnt vmcnt(8)
	s_waitcnt lgkmcnt(0)
	s_barrier
	s_setprio 1
	s_waitcnt lgkmcnt(0)
	v_mfma_f32_16x16x32_bf16 v[128:131], v[150:153], v[182:185], v[128:131]
	v_mfma_f32_16x16x32_bf16 v[124:127], v[158:161], v[182:185], v[124:127]
	v_mfma_f32_16x16x32_bf16 v[112:115], v[150:153], v[190:193], v[112:115]
	v_mfma_f32_16x16x32_bf16 v[108:111], v[158:161], v[190:193], v[108:111]
	v_mfma_f32_16x16x32_bf16 v[96:99], v[150:153], v[214:217], v[96:99]
	v_mfma_f32_16x16x32_bf16 v[92:95], v[158:161], v[214:217], v[92:95]
	v_mfma_f32_16x16x32_bf16 v[80:83], v[150:153], v[222:225], v[80:83]
	v_mfma_f32_16x16x32_bf16 v[76:79], v[158:161], v[222:225], v[76:79]
	v_mfma_f32_16x16x32_bf16 v[128:131], v[154:157], v[186:189], v[128:131]
	v_mfma_f32_16x16x32_bf16 v[124:127], v[162:165], v[186:189], v[124:127]
	v_mfma_f32_16x16x32_bf16 v[112:115], v[154:157], v[210:213], v[112:115]
	v_mfma_f32_16x16x32_bf16 v[108:111], v[162:165], v[210:213], v[108:111]
	v_mfma_f32_16x16x32_bf16 v[96:99], v[154:157], v[218:221], v[96:99]
	v_mfma_f32_16x16x32_bf16 v[92:95], v[162:165], v[218:221], v[92:95]
	v_mfma_f32_16x16x32_bf16 v[80:83], v[154:157], v[226:229], v[80:83]
	v_mfma_f32_16x16x32_bf16 v[76:79], v[162:165], v[226:229], v[76:79]
	s_setprio 0
	s_setprio 1
	v_mfma_f32_16x16x32_bf16 v[120:123], v[166:169], v[182:185], v[120:123]
	v_mfma_f32_16x16x32_bf16 v[116:119], v[174:177], v[182:185], v[116:119]
	v_mfma_f32_16x16x32_bf16 v[104:107], v[166:169], v[190:193], v[104:107]
	v_mfma_f32_16x16x32_bf16 v[100:103], v[174:177], v[190:193], v[100:103]
	v_mfma_f32_16x16x32_bf16 v[88:91], v[166:169], v[214:217], v[88:91]
	v_mfma_f32_16x16x32_bf16 v[84:87], v[174:177], v[214:217], v[84:87]
	v_mfma_f32_16x16x32_bf16 v[72:75], v[166:169], v[222:225], v[72:75]
	v_mfma_f32_16x16x32_bf16 v[68:71], v[174:177], v[222:225], v[68:71]
	v_mfma_f32_16x16x32_bf16 v[120:123], v[170:173], v[186:189], v[120:123]
	v_mfma_f32_16x16x32_bf16 v[116:119], v[178:181], v[186:189], v[116:119]
	v_mfma_f32_16x16x32_bf16 v[104:107], v[170:173], v[210:213], v[104:107]
	v_mfma_f32_16x16x32_bf16 v[100:103], v[178:181], v[210:213], v[100:103]
	v_mfma_f32_16x16x32_bf16 v[88:91], v[170:173], v[218:221], v[88:91]
	v_mfma_f32_16x16x32_bf16 v[84:87], v[178:181], v[218:221], v[84:87]
	v_mfma_f32_16x16x32_bf16 v[72:75], v[170:173], v[226:229], v[72:75]
	v_mfma_f32_16x16x32_bf16 v[68:71], v[178:181], v[226:229], v[68:71]
	s_setprio 0
	s_barrier
	s_add_i32 s64, s64, s24
	v_lshl_add_u64 v[144:145], s[20:21], 0, v[136:137]
	s_mov_b32 m0, s64
	ds_read_b128 v[182:185], v148 offset:16384
	ds_read_b128 v[186:189], v148 offset:17408
	ds_read_b128 v[190:193], v148 offset:18432
	ds_read_b128 v[210:213], v148 offset:19456
	ds_read_b128 v[214:217], v148 offset:20480
	ds_read_b128 v[218:221], v148 offset:21504
	ds_read_b128 v[222:225], v148 offset:22528
	ds_read_b128 v[226:229], v148 offset:23552
	global_load_lds_dwordx4 v[144:145], off
	s_add_i32 m0, s64, 0x2000
	s_add_u32 s64, s20, 0x40000
	v_lshl_add_u64 v[194:195], s[20:21], 0, v[132:133]
	s_addc_u32 s65, s21, 0
	s_add_i32 s66, s66, s24
	global_load_lds_dwordx4 v[194:195], off
	v_lshl_add_u64 v[246:247], s[64:65], 0, v[136:137]
	s_mov_b32 m0, s66
	v_lshl_add_u64 v[248:249], s[22:23], 0, v[134:135]
	global_load_lds_dwordx4 v[246:247], off
	v_lshl_add_u64 v[246:247], s[64:65], 0, v[132:133]
	s_add_i32 m0, s66, 0x2000
	s_nop 0
	global_load_lds_dwordx4 v[246:247], off
	v_lshl_add_u64 v[246:247], s[22:23], 0, v[138:139]
	s_mov_b32 m0, s29
	s_nop 0
	global_load_lds_dwordx4 v[246:247], off
	s_mov_b32 m0, s30
	s_nop 0
	global_load_lds_dwordx4 v[248:249], off
	s_waitcnt vmcnt(8)
	s_waitcnt lgkmcnt(0)
	s_barrier
; #define PG8_STAGE(bufoff, gbase, voff) do { _Pragma("unroll") for (int _i = 0; _i < 2; ++_i) \
;         __builtin_amdgcn_global_load_lds((const unsigned*)((const char*)(gbase) + (voff)[_i]), (PG8_LAS unsigned*)(lds + (bufoff) + ldsw + _i * 8192), 16, 0, 0); } while (0)
; #define PG8_LDA(dst, b, h) do { _Pragma("unroll") for (int m = 0; m < 4; ++m) _Pragma("unroll") for (int k = 0; k < 2; ++k) dst[m][k] = *(const PG8_LAS bf16x8*)(lds + PG8_SA(b, h) + aoff + m * 2048 + k * 1024); } while (0)
; #define PG8_LDB(dst, b, h) do { _Pragma("unroll") for (int n = 0; n < 2; ++n) _Pragma("unroll") for (int k = 0; k < 2; ++k) dst[n][k] = *(const PG8_LAS bf16x8*)(lds + PG8_SB(b, h) + boff + n * 2048 + k * 1024); } while (0)
; #define PG8_MMA(ai, bj, At, Bt) do { __builtin_amdgcn_s_setprio(1); _Pragma("unroll") for (int m = 0; m < 4; ++m) _Pragma("unroll") for (int n = 0; n < 2; ++n) _Pragma("unroll") for (int k = 0; k < 2; ++k) \
;         acc[ai][bj][m][n] = __builtin_amdgcn_mfma_f32_16x16x32_bf16(Bt[n][k], At[m][k], acc[ai][bj][m][n], 0, 0, 0); __builtin_amdgcn_s_setprio(0); } while (0)
; #define PG8_WAIT_V(n) asm volatile("s_waitcnt vmcnt(" #n ")" ::: "memory")
; #define PG8_WAIT_L(n) asm volatile("s_waitcnt lgkmcnt(" #n ")" ::: "memory")
; #define PG8_BAR __builtin_amdgcn_s_barrier()
; #define PG8_SCHED __builtin_amdgcn_sched_barrier(0)
; template <class Epi, class Sched, bool ALIGN_EPI = false, bool SP2 = false>
; __device__ __forceinline__ void gemm_phase(PG8_LAS unsigned char* lds, const Gemm g, const Sched& S, const Epi& E) {
;     ...
;             PG8_WAIT_V(8); PG8_WAIT_L(0); PG8_BAR; PG8_MMA(1, 0, At, B0); PG8_MMA(1, 1, At, B1); PG8_BAR; PG8_SCHED;
;             PG8_LDB(B0, 1, 0); PG8_LDB(B1, 1, 1); PG8_SCHED; PG8_LDA(At, 1, 0); PG8_STAGE(PG8_SA(0, 1), a2 + hstep, voffA);
;             PG8_WAIT_V(8); PG8_WAIT_L(0); PG8_BAR; PG8_MMA(0, 0, At, B0); PG8_MMA(0, 1, At, B1); PG8_BAR; PG8_SCHED;
	s_setprio 1
	s_waitcnt lgkmcnt(0)
	v_mfma_f32_16x16x32_bf16 v[64:67], v[150:153], v[182:185], v[64:67]
	v_mfma_f32_16x16x32_bf16 v[60:63], v[158:161], v[182:185], v[60:63]
	v_mfma_f32_16x16x32_bf16 v[48:51], v[150:153], v[190:193], v[48:51]
	v_mfma_f32_16x16x32_bf16 v[44:47], v[158:161], v[190:193], v[44:47]
	v_mfma_f32_16x16x32_bf16 v[32:35], v[150:153], v[214:217], v[32:35]
	v_mfma_f32_16x16x32_bf16 v[28:31], v[158:161], v[214:217], v[28:31]
	v_mfma_f32_16x16x32_bf16 v[16:19], v[150:153], v[222:225], v[16:19]
	v_mfma_f32_16x16x32_bf16 v[12:15], v[158:161], v[222:225], v[12:15]
	v_mfma_f32_16x16x32_bf16 v[64:67], v[154:157], v[186:189], v[64:67]
	v_mfma_f32_16x16x32_bf16 v[60:63], v[162:165], v[186:189], v[60:63]
	v_mfma_f32_16x16x32_bf16 v[48:51], v[154:157], v[210:213], v[48:51]
	v_mfma_f32_16x16x32_bf16 v[44:47], v[162:165], v[210:213], v[44:47]
	v_mfma_f32_16x16x32_bf16 v[32:35], v[154:157], v[218:221], v[32:35]
	v_mfma_f32_16x16x32_bf16 v[28:31], v[162:165], v[218:221], v[28:31]
	v_mfma_f32_16x16x32_bf16 v[16:19], v[154:157], v[226:229], v[16:19]
	v_mfma_f32_16x16x32_bf16 v[12:15], v[162:165], v[226:229], v[12:15]
	s_setprio 0
	s_setprio 1
	v_mfma_f32_16x16x32_bf16 v[56:59], v[166:169], v[182:185], v[56:59]
	v_mfma_f32_16x16x32_bf16 v[52:55], v[174:177], v[182:185], v[52:55]
	v_mfma_f32_16x16x32_bf16 v[40:43], v[166:169], v[190:193], v[40:43]
	v_mfma_f32_16x16x32_bf16 v[36:39], v[174:177], v[190:193], v[36:39]
	v_mfma_f32_16x16x32_bf16 v[24:27], v[166:169], v[214:217], v[24:27]
	v_mfma_f32_16x16x32_bf16 v[20:23], v[174:177], v[214:217], v[20:23]
	v_mfma_f32_16x16x32_bf16 v[8:11], v[166:169], v[222:225], v[8:11]
	v_mfma_f32_16x16x32_bf16 v[4:7], v[174:177], v[222:225], v[4:7]
	v_mfma_f32_16x16x32_bf16 v[56:59], v[170:173], v[186:189], v[56:59]
	v_mfma_f32_16x16x32_bf16 v[52:55], v[178:181], v[186:189], v[52:55]
	v_mfma_f32_16x16x32_bf16 v[40:43], v[170:173], v[210:213], v[40:43]
	v_mfma_f32_16x16x32_bf16 v[36:39], v[178:181], v[210:213], v[36:39]
	v_mfma_f32_16x16x32_bf16 v[24:27], v[170:173], v[218:221], v[24:27]
	v_mfma_f32_16x16x32_bf16 v[20:23], v[178:181], v[218:221], v[20:23]
	v_mfma_f32_16x16x32_bf16 v[8:11], v[170:173], v[226:229], v[8:11]
	v_mfma_f32_16x16x32_bf16 v[4:7], v[178:181], v[226:229], v[4:7]
	s_setprio 0
	s_barrier
	s_add_i32 s64, 0, 0x18000
	v_add_u32_e32 v149, s64, v146
	s_add_i32 s65, 0, 0x1c000
	ds_read_b128 v[150:153], v149
	ds_read_b128 v[154:157], v149 offset:1024
	ds_read_b128 v[158:161], v149 offset:2048
	ds_read_b128 v[162:165], v149 offset:3072
	v_add_u32_e32 v149, s65, v146
	ds_read_b128 v[166:169], v149
	ds_read_b128 v[170:173], v149 offset:1024
	ds_read_b128 v[174:177], v149 offset:2048
	ds_read_b128 v[178:181], v149 offset:3072
	s_add_u32 s22, s22, 0x40000
	s_addc_u32 s23, s23, 0
	s_mov_b32 m0, s31
	v_lshl_add_u64 v[250:251], s[22:23], 0, v[138:139]
	ds_read_b128 v[182:185], v148 offset:32768
	ds_read_b128 v[186:189], v148 offset:33792
	ds_read_b128 v[190:193], v148 offset:34816
	ds_read_b128 v[210:213], v148 offset:35840
	ds_read_b128 v[214:217], v148 offset:36864
	ds_read_b128 v[218:221], v148 offset:37888
	ds_read_b128 v[222:225], v148 offset:38912
	ds_read_b128 v[226:229], v148 offset:39936
	global_load_lds_dwordx4 v[250:251], off
	v_lshl_add_u64 v[250:251], s[22:23], 0, v[134:135]
	s_mov_b32 m0, s34
	s_nop 0
	global_load_lds_dwordx4 v[250:251], off
	s_waitcnt vmcnt(8)
	s_waitcnt lgkmcnt(0)
	s_barrier
	s_setprio 1
	s_waitcnt lgkmcnt(0)
	v_mfma_f32_16x16x32_bf16 v[128:131], v[150:153], v[182:185], v[128:131]
	v_mfma_f32_16x16x32_bf16 v[124:127], v[158:161], v[182:185], v[124:127]
	v_mfma_f32_16x16x32_bf16 v[112:115], v[150:153], v[190:193], v[112:115]
	v_mfma_f32_16x16x32_bf16 v[108:111], v[158:161], v[190:193], v[108:111]
	v_mfma_f32_16x16x32_bf16 v[96:99], v[150:153], v[214:217], v[96:99]
	v_mfma_f32_16x16x32_bf16 v[92:95], v[158:161], v[214:217], v[92:95]
	v_mfma_f32_16x16x32_bf16 v[80:83], v[150:153], v[222:225], v[80:83]
	v_mfma_f32_16x16x32_bf16 v[76:79], v[158:161], v[222:225], v[76:79]
	v_mfma_f32_16x16x32_bf16 v[128:131], v[154:157], v[186:189], v[128:131]
	v_mfma_f32_16x16x32_bf16 v[124:127], v[162:165], v[186:189], v[124:127]
	v_mfma_f32_16x16x32_bf16 v[112:115], v[154:157], v[210:213], v[112:115]
	v_mfma_f32_16x16x32_bf16 v[108:111], v[162:165], v[210:213], v[108:111]
	v_mfma_f32_16x16x32_bf16 v[96:99], v[154:157], v[218:221], v[96:99]
	v_mfma_f32_16x16x32_bf16 v[92:95], v[162:165], v[218:221], v[92:95]
	v_mfma_f32_16x16x32_bf16 v[80:83], v[154:157], v[226:229], v[80:83]
	v_mfma_f32_16x16x32_bf16 v[76:79], v[162:165], v[226:229], v[76:79]
	s_setprio 0
	s_setprio 1
	v_mfma_f32_16x16x32_bf16 v[120:123], v[166:169], v[182:185], v[120:123]
	v_mfma_f32_16x16x32_bf16 v[116:119], v[174:177], v[182:185], v[116:119]
	v_mfma_f32_16x16x32_bf16 v[104:107], v[166:169], v[190:193], v[104:107]
	v_mfma_f32_16x16x32_bf16 v[100:103], v[174:177], v[190:193], v[100:103]
	v_mfma_f32_16x16x32_bf16 v[88:91], v[166:169], v[214:217], v[88:91]
	v_mfma_f32_16x16x32_bf16 v[84:87], v[174:177], v[214:217], v[84:87]
	v_mfma_f32_16x16x32_bf16 v[72:75], v[166:169], v[222:225], v[72:75]
	v_mfma_f32_16x16x32_bf16 v[68:71], v[174:177], v[222:225], v[68:71]
	v_mfma_f32_16x16x32_bf16 v[120:123], v[170:173], v[186:189], v[120:123]
	v_mfma_f32_16x16x32_bf16 v[116:119], v[178:181], v[186:189], v[116:119]
	v_mfma_f32_16x16x32_bf16 v[104:107], v[170:173], v[210:213], v[104:107]
	v_mfma_f32_16x16x32_bf16 v[100:103], v[178:181], v[210:213], v[100:103]
	v_mfma_f32_16x16x32_bf16 v[88:91], v[170:173], v[218:221], v[88:91]
	v_mfma_f32_16x16x32_bf16 v[84:87], v[178:181], v[218:221], v[84:87]
	v_mfma_f32_16x16x32_bf16 v[72:75], v[170:173], v[226:229], v[72:75]
	v_mfma_f32_16x16x32_bf16 v[68:71], v[178:181], v[226:229], v[68:71]
	s_setprio 0
	s_barrier
; #define PG8_STAGE(bufoff, gbase, voff) do { _Pragma("unroll") for (int _i = 0; _i < 2; ++_i) \
;         __builtin_amdgcn_global_load_lds((const unsigned*)((const char*)(gbase) + (voff)[_i]), (PG8_LAS unsigned*)(lds + (bufoff) + ldsw + _i * 8192), 16, 0, 0); } while (0)
; #define PG8_LDA(dst, b, h) do { _Pragma("unroll") for (int m = 0; m < 4; ++m) _Pragma("unroll") for (int k = 0; k < 2; ++k) dst[m][k] = *(const PG8_LAS bf16x8*)(lds + PG8_SA(b, h) + aoff + m * 2048 + k * 1024); } while (0)
; #define PG8_MMA(ai, bj, At, Bt) do { __builtin_amdgcn_s_setprio(1); _Pragma("unroll") for (int m = 0; m < 4; ++m) _Pragma("unroll") for (int n = 0; n < 2; ++n) _Pragma("unroll") for (int k = 0; k < 2; ++k) \
;         acc[ai][bj][m][n] = __builtin_amdgcn_mfma_f32_16x16x32_bf16(Bt[n][k], At[m][k], acc[ai][bj][m][n], 0, 0, 0); __builtin_amdgcn_s_setprio(0); } while (0)
; #define PG8_WAIT_V(n) asm volatile("s_waitcnt vmcnt(" #n ")" ::: "memory")
; #define PG8_WAIT_L(n) asm volatile("s_waitcnt lgkmcnt(" #n ")" ::: "memory")
; #define PG8_BAR __builtin_amdgcn_s_barrier()
; #define PG8_SCHED __builtin_amdgcn_sched_barrier(0)
; template <class Epi, class Sched, bool ALIGN_EPI = false, bool SP2 = false>
; __device__ __forceinline__ void gemm_phase(PG8_LAS unsigned char* lds, const Gemm g, const Sched& S, const Epi& E) {
;     ...
;         for (int t = 0; t < nt; t += 2) {
;     ...
;             PG8_LDA(At, 1, 1); PG8_STAGE(PG8_SB(1, 0), b3, voffB); PG8_STAGE(PG8_SB(1, 1), b3 + hstep, voffB); PG8_STAGE(PG8_SA(1, 0), a3, voffA);
;             PG8_WAIT_V(8); PG8_WAIT_L(0); PG8_BAR; PG8_MMA(1, 0, At, B0); PG8_MMA(1, 1, At, B1); PG8_BAR; PG8_SCHED;
	s_add_i32 s22, s64, s24
	v_lshl_add_u64 v[144:145], v[144:145], 0, s[78:79]
	s_mov_b32 m0, s22
	ds_read_b128 v[182:185], v148 offset:49152
	ds_read_b128 v[186:189], v148 offset:50176
	ds_read_b128 v[190:193], v148 offset:51200
	ds_read_b128 v[210:213], v148 offset:52224
	ds_read_b128 v[214:217], v148 offset:53248
	ds_read_b128 v[218:221], v148 offset:54272
	ds_read_b128 v[222:225], v148 offset:55296
	ds_read_b128 v[226:229], v148 offset:56320
	global_load_lds_dwordx4 v[144:145], off
	s_add_i32 m0, s22, 0x2000
	s_add_u32 s20, s20, 0x40080
	v_lshl_add_u64 v[144:145], v[194:195], 0, s[78:79]
	s_addc_u32 s21, s21, 0
	s_add_i32 s22, s65, s24
	global_load_lds_dwordx4 v[144:145], off
	v_lshl_add_u64 v[144:145], s[20:21], 0, v[136:137]
	s_mov_b32 m0, s22
	s_nop 0
	global_load_lds_dwordx4 v[144:145], off
	v_lshl_add_u64 v[144:145], s[20:21], 0, v[132:133]
	s_add_i32 m0, s22, 0x2000
	s_nop 0
	global_load_lds_dwordx4 v[144:145], off
	v_lshl_add_u64 v[144:145], v[246:247], 0, s[78:79]
	s_mov_b32 m0, s35
	s_nop 0
	global_load_lds_dwordx4 v[144:145], off
	v_lshl_add_u64 v[144:145], v[248:249], 0, s[78:79]
	s_mov_b32 m0, s36
	s_nop 0
	global_load_lds_dwordx4 v[144:145], off
	s_waitcnt vmcnt(8)
	s_waitcnt lgkmcnt(0)
	s_barrier
	s_setprio 1
	s_waitcnt lgkmcnt(0)
	v_mfma_f32_16x16x32_bf16 v[64:67], v[150:153], v[182:185], v[64:67]
	v_mfma_f32_16x16x32_bf16 v[60:63], v[158:161], v[182:185], v[60:63]
	v_mfma_f32_16x16x32_bf16 v[48:51], v[150:153], v[190:193], v[48:51]
	v_mfma_f32_16x16x32_bf16 v[44:47], v[158:161], v[190:193], v[44:47]
	v_mfma_f32_16x16x32_bf16 v[32:35], v[150:153], v[214:217], v[32:35]
	v_mfma_f32_16x16x32_bf16 v[28:31], v[158:161], v[214:217], v[28:31]
	v_mfma_f32_16x16x32_bf16 v[16:19], v[150:153], v[222:225], v[16:19]
	v_mfma_f32_16x16x32_bf16 v[12:15], v[158:161], v[222:225], v[12:15]
	v_mfma_f32_16x16x32_bf16 v[64:67], v[154:157], v[186:189], v[64:67]
	v_mfma_f32_16x16x32_bf16 v[60:63], v[162:165], v[186:189], v[60:63]
	v_mfma_f32_16x16x32_bf16 v[48:51], v[154:157], v[210:213], v[48:51]
	v_mfma_f32_16x16x32_bf16 v[44:47], v[162:165], v[210:213], v[44:47]
	v_mfma_f32_16x16x32_bf16 v[32:35], v[154:157], v[218:221], v[32:35]
	v_mfma_f32_16x16x32_bf16 v[28:31], v[162:165], v[218:221], v[28:31]
	v_mfma_f32_16x16x32_bf16 v[16:19], v[154:157], v[226:229], v[16:19]
	v_mfma_f32_16x16x32_bf16 v[12:15], v[162:165], v[226:229], v[12:15]
	s_setprio 0
	s_setprio 1
	v_mfma_f32_16x16x32_bf16 v[56:59], v[166:169], v[182:185], v[56:59]
	v_mfma_f32_16x16x32_bf16 v[52:55], v[174:177], v[182:185], v[52:55]
	v_mfma_f32_16x16x32_bf16 v[40:43], v[166:169], v[190:193], v[40:43]
	v_mfma_f32_16x16x32_bf16 v[36:39], v[174:177], v[190:193], v[36:39]
	v_mfma_f32_16x16x32_bf16 v[24:27], v[166:169], v[214:217], v[24:27]
	v_mfma_f32_16x16x32_bf16 v[20:23], v[174:177], v[214:217], v[20:23]
	v_mfma_f32_16x16x32_bf16 v[8:11], v[166:169], v[222:225], v[8:11]
	v_mfma_f32_16x16x32_bf16 v[4:7], v[174:177], v[222:225], v[4:7]
	v_mfma_f32_16x16x32_bf16 v[56:59], v[170:173], v[186:189], v[56:59]
	v_mfma_f32_16x16x32_bf16 v[52:55], v[178:181], v[186:189], v[52:55]
	v_mfma_f32_16x16x32_bf16 v[40:43], v[170:173], v[210:213], v[40:43]
	v_mfma_f32_16x16x32_bf16 v[36:39], v[178:181], v[210:213], v[36:39]
	v_mfma_f32_16x16x32_bf16 v[24:27], v[170:173], v[218:221], v[24:27]
	v_mfma_f32_16x16x32_bf16 v[20:23], v[178:181], v[218:221], v[20:23]
	v_mfma_f32_16x16x32_bf16 v[8:11], v[170:173], v[226:229], v[8:11]
	v_mfma_f32_16x16x32_bf16 v[4:7], v[178:181], v[226:229], v[4:7]
	s_setprio 0
	s_add_i32 s55, s55, 2
	s_add_u32 s18, s18, 0x100
	s_addc_u32 s19, s19, 0
	s_add_u32 s53, s53, 0x100
	s_addc_u32 s54, s54, 0
	s_cmp_gt_u32 s55, 13
	s_barrier
	s_cbranch_scc0 .LBB0_931
	s_and_b64 vcc, exec, s[8:9]
	s_cbranch_vccz .LBB0_934
	s_barrier

; #define PG8_STAGE(bufoff, gbase, voff) do { _Pragma("unroll") for (int _i = 0; _i < 2; ++_i) \
;         __builtin_amdgcn_global_load_lds((const unsigned*)((const char*)(gbase) + (voff)[_i]), (PG8_LAS unsigned*)(lds + (bufoff) + ldsw + _i * 8192), 16, 0, 0); } while (0)
; #define PG8_LDA(dst, b, h) do { _Pragma("unroll") for (int m = 0; m < 4; ++m) _Pragma("unroll") for (int k = 0; k < 2; ++k) dst[m][k] = *(const PG8_LAS bf16x8*)(lds + PG8_SA(b, h) + aoff + m * 2048 + k * 1024); } while (0)
; #define PG8_LDB(dst, b, h) do { _Pragma("unroll") for (int n = 0; n < 2; ++n) _Pragma("unroll") for (int k = 0; k < 2; ++k) dst[n][k] = *(const PG8_LAS bf16x8*)(lds + PG8_SB(b, h) + boff + n * 2048 + k * 1024); } while (0)
; #define PG8_MMA(ai, bj, At, Bt) do { __builtin_amdgcn_s_setprio(1); _Pragma("unroll") for (int m = 0; m < 4; ++m) _Pragma("unroll") for (int n = 0; n < 2; ++n) _Pragma("unroll") for (int k = 0; k < 2; ++k) \
;         acc[ai][bj][m][n] = __builtin_amdgcn_mfma_f32_16x16x32_bf16(Bt[n][k], At[m][k], acc[ai][bj][m][n], 0, 0, 0); __builtin_amdgcn_s_setprio(0); } while (0)
; #define PG8_WAIT_V(n) asm volatile("s_waitcnt vmcnt(" #n ")" ::: "memory")
; #define PG8_WAIT_L(n) asm volatile("s_waitcnt lgkmcnt(" #n ")" ::: "memory")
; template <class Epi, class Sched, bool ALIGN_EPI = false, bool SP2 = false>
; __device__ __forceinline__ void gemm_phase(PG8_LAS unsigned char* lds, const Gemm g, const Sched& S, const Epi& E) {
;     ...
;             const bool last = (t == nt - 2);
;             const char* a1 = cA + (size_t)(t + 1) * kstep;
;             const char* a2 = last ? nA : cA + (size_t)(t + 2) * kstep; const char* b2 = last ? nB : cB + (size_t)(t + 2) * kstep;
;             const char* a3 = a2 + kstep; const char* b3 = b2 + kstep;
;             if (last && has_next) S.a_ready(nxt);
;             if constexpr (SP2) {
;             PG8_LDB(B0, 0, 0); PG8_LDB(B1, 0, 1); PG8_SCHED; PG8_LDA(At, 0, 0); PG8_STAGE(PG8_SA(1, 1), a1 + hstep, voffA);
;             PG8_WAIT_V(8); PG8_WAIT_L(0); PG8_BAR; PG8_MMA(0, 0, At, B0); PG8_MMA(0, 1, At, B1); PG8_BAR; PG8_SCHED;
;             PG8_LDA(At, 0, 1); PG8_STAGE(PG8_SB(0, 0), b2, voffB); PG8_STAGE(PG8_SB(0, 1), b2 + hstep, voffB); PG8_STAGE(PG8_SA(0, 0), a2, voffA);
;             PG8_WAIT_V(8); PG8_WAIT_L(0); PG8_BAR; PG8_MMA(1, 0, At, B0); PG8_MMA(1, 1, At, B1); PG8_BAR; PG8_SCHED;
.LBB0_1007:
	s_add_u32 s20, s18, 0x100
	s_addc_u32 s21, s19, 0
	s_add_i32 s66, 0, 0x10000
	s_cmp_eq_u32 s72, 40
	s_cselect_b32 s25, s1, s21
	s_cselect_b32 s24, s0, s20
	s_cselect_b32 s23, s17, s65
	s_cselect_b32 s22, s16, s64
	s_add_i32 s67, 0, 0x14000
	v_add_u32_e32 v136, s66, v226
	v_add_u32_e32 v160, s67, v226
	ds_read_b128 v[116:119], v136
	ds_read_b128 v[120:123], v136 offset:1024
	ds_read_b128 v[132:135], v136 offset:2048
	ds_read_b128 v[136:139], v136 offset:3072
	ds_read_b128 v[144:147], v160
	ds_read_b128 v[152:155], v160 offset:1024
	ds_read_b128 v[156:159], v160 offset:2048
	ds_read_b128 v[160:163], v160 offset:3072
	v_lshl_add_u64 v[220:221], s[18:19], 0, v[216:217]
	s_add_i32 m0, s34, 0xc000
	ds_read_b128 v[164:167], v228
	ds_read_b128 v[168:171], v228 offset:1024
	ds_read_b128 v[172:175], v228 offset:2048
	ds_read_b128 v[176:179], v228 offset:3072
	ds_read_b128 v[180:183], v228 offset:4096
	ds_read_b128 v[184:187], v228 offset:5120
	ds_read_b128 v[188:191], v228 offset:6144
	ds_read_b128 v[192:195], v228 offset:7168
	global_load_lds_dwordx4 v[220:221], off
	v_lshl_add_u64 v[220:221], s[18:19], 0, v[218:219]
	s_add_i32 m0, s34, 0xe000
	s_nop 0
	global_load_lds_dwordx4 v[220:221], off
	s_waitcnt vmcnt(8)
	s_waitcnt lgkmcnt(0)
	s_barrier
	s_setprio 1
	s_waitcnt lgkmcnt(0)
	v_mfma_f32_16x16x32_bf16 v[148:151], v[116:119], v[164:167], v[148:151]
	v_mfma_f32_16x16x32_bf16 v[140:143], v[132:135], v[164:167], v[140:143]
	v_mfma_f32_16x16x32_bf16 v[112:115], v[116:119], v[172:175], v[112:115]
	v_mfma_f32_16x16x32_bf16 v[108:111], v[132:135], v[172:175], v[108:111]
	v_mfma_f32_16x16x32_bf16 v[96:99], v[116:119], v[180:183], v[96:99]
	v_mfma_f32_16x16x32_bf16 v[92:95], v[132:135], v[180:183], v[92:95]
	v_mfma_f32_16x16x32_bf16 v[80:83], v[116:119], v[188:191], v[80:83]
	v_mfma_f32_16x16x32_bf16 v[76:79], v[132:135], v[188:191], v[76:79]
	v_mfma_f32_16x16x32_bf16 v[148:151], v[120:123], v[168:171], v[148:151]
	v_mfma_f32_16x16x32_bf16 v[140:143], v[136:139], v[168:171], v[140:143]
	v_mfma_f32_16x16x32_bf16 v[112:115], v[120:123], v[176:179], v[112:115]
	v_mfma_f32_16x16x32_bf16 v[108:111], v[136:139], v[176:179], v[108:111]
	v_mfma_f32_16x16x32_bf16 v[96:99], v[120:123], v[184:187], v[96:99]
	v_mfma_f32_16x16x32_bf16 v[92:95], v[136:139], v[184:187], v[92:95]
	v_mfma_f32_16x16x32_bf16 v[80:83], v[120:123], v[192:195], v[80:83]
	v_mfma_f32_16x16x32_bf16 v[76:79], v[136:139], v[192:195], v[76:79]
	s_setprio 0
	s_setprio 1
	v_mfma_f32_16x16x32_bf16 v[128:131], v[144:147], v[164:167], v[128:131]
	v_mfma_f32_16x16x32_bf16 v[124:127], v[156:159], v[164:167], v[124:127]
	v_mfma_f32_16x16x32_bf16 v[104:107], v[144:147], v[172:175], v[104:107]
	v_mfma_f32_16x16x32_bf16 v[100:103], v[156:159], v[172:175], v[100:103]
	v_mfma_f32_16x16x32_bf16 v[88:91], v[144:147], v[180:183], v[88:91]
	v_mfma_f32_16x16x32_bf16 v[84:87], v[156:159], v[180:183], v[84:87]
	v_mfma_f32_16x16x32_bf16 v[72:75], v[144:147], v[188:191], v[72:75]
	v_mfma_f32_16x16x32_bf16 v[68:71], v[156:159], v[188:191], v[68:71]
	v_mfma_f32_16x16x32_bf16 v[128:131], v[152:155], v[168:171], v[128:131]
	v_mfma_f32_16x16x32_bf16 v[124:127], v[160:163], v[168:171], v[124:127]
	v_mfma_f32_16x16x32_bf16 v[104:107], v[152:155], v[176:179], v[104:107]
	v_mfma_f32_16x16x32_bf16 v[100:103], v[160:163], v[176:179], v[100:103]
	v_mfma_f32_16x16x32_bf16 v[88:91], v[152:155], v[184:187], v[88:91]
	v_mfma_f32_16x16x32_bf16 v[84:87], v[160:163], v[184:187], v[84:87]
	v_mfma_f32_16x16x32_bf16 v[72:75], v[152:155], v[192:195], v[72:75]
	v_mfma_f32_16x16x32_bf16 v[68:71], v[160:163], v[192:195], v[68:71]
	s_setprio 0
	s_barrier
	s_add_i32 s18, s66, s31
	v_lshl_add_u64 v[220:221], s[22:23], 0, v[196:197]
	s_mov_b32 m0, s18
	ds_read_b128 v[164:167], v228 offset:16384
	ds_read_b128 v[168:171], v228 offset:17408
	ds_read_b128 v[172:175], v228 offset:18432
	ds_read_b128 v[176:179], v228 offset:19456
	ds_read_b128 v[180:183], v228 offset:20480
	ds_read_b128 v[184:187], v228 offset:21504
	ds_read_b128 v[188:191], v228 offset:22528
	ds_read_b128 v[192:195], v228 offset:23552
	global_load_lds_dwordx4 v[220:221], off
	s_add_i32 m0, s18, 0x2000
	s_add_u32 s18, s22, 0xb0000
	v_lshl_add_u64 v[222:223], s[22:23], 0, v[210:211]
	s_addc_u32 s19, s23, 0
	s_add_i32 s66, s67, s31
	global_load_lds_dwordx4 v[222:223], off
	v_lshl_add_u64 v[224:225], s[18:19], 0, v[196:197]
	s_mov_b32 m0, s66
	v_lshl_add_u64 v[246:247], s[24:25], 0, v[212:213]
	global_load_lds_dwordx4 v[224:225], off
	v_lshl_add_u64 v[224:225], s[18:19], 0, v[210:211]
	s_add_i32 m0, s66, 0x2000
	s_nop 0
	global_load_lds_dwordx4 v[224:225], off
	v_lshl_add_u64 v[224:225], s[24:25], 0, v[214:215]
	s_mov_b32 m0, s34
	s_nop 0
	global_load_lds_dwordx4 v[224:225], off
	s_mov_b32 m0, s35
	s_nop 0
	global_load_lds_dwordx4 v[246:247], off
	s_waitcnt vmcnt(8)
	s_waitcnt lgkmcnt(0)
	s_barrier
; #define PG8_STAGE(bufoff, gbase, voff) do { _Pragma("unroll") for (int _i = 0; _i < 2; ++_i) \
;         __builtin_amdgcn_global_load_lds((const unsigned*)((const char*)(gbase) + (voff)[_i]), (PG8_LAS unsigned*)(lds + (bufoff) + ldsw + _i * 8192), 16, 0, 0); } while (0)
; #define PG8_LDA(dst, b, h) do { _Pragma("unroll") for (int m = 0; m < 4; ++m) _Pragma("unroll") for (int k = 0; k < 2; ++k) dst[m][k] = *(const PG8_LAS bf16x8*)(lds + PG8_SA(b, h) + aoff + m * 2048 + k * 1024); } while (0)
; #define PG8_LDB(dst, b, h) do { _Pragma("unroll") for (int n = 0; n < 2; ++n) _Pragma("unroll") for (int k = 0; k < 2; ++k) dst[n][k] = *(const PG8_LAS bf16x8*)(lds + PG8_SB(b, h) + boff + n * 2048 + k * 1024); } while (0)
; #define PG8_MMA(ai, bj, At, Bt) do { __builtin_amdgcn_s_setprio(1); _Pragma("unroll") for (int m = 0; m < 4; ++m) _Pragma("unroll") for (int n = 0; n < 2; ++n) _Pragma("unroll") for (int k = 0; k < 2; ++k) \
;         acc[ai][bj][m][n] = __builtin_amdgcn_mfma_f32_16x16x32_bf16(Bt[n][k], At[m][k], acc[ai][bj][m][n], 0, 0, 0); __builtin_amdgcn_s_setprio(0); } while (0)
; #define PG8_WAIT_V(n) asm volatile("s_waitcnt vmcnt(" #n ")" ::: "memory")
; #define PG8_WAIT_L(n) asm volatile("s_waitcnt lgkmcnt(" #n ")" ::: "memory")
; #define PG8_BAR __builtin_amdgcn_s_barrier()
; #define PG8_SCHED __builtin_amdgcn_sched_barrier(0)
; template <class Epi, class Sched, bool ALIGN_EPI = false, bool SP2 = false>
; __device__ __forceinline__ void gemm_phase(PG8_LAS unsigned char* lds, const Gemm g, const Sched& S, const Epi& E) {
;     ...
;             PG8_WAIT_V(8); PG8_WAIT_L(0); PG8_BAR; PG8_MMA(1, 0, At, B0); PG8_MMA(1, 1, At, B1); PG8_BAR; PG8_SCHED;
;             PG8_LDB(B0, 1, 0); PG8_LDB(B1, 1, 1); PG8_SCHED; PG8_LDA(At, 1, 0); PG8_STAGE(PG8_SA(0, 1), a2 + hstep, voffA);
;             PG8_WAIT_V(8); PG8_WAIT_L(0); PG8_BAR; PG8_MMA(0, 0, At, B0); PG8_MMA(0, 1, At, B1); PG8_BAR; PG8_SCHED;
	s_setprio 1
	s_waitcnt lgkmcnt(0)
	v_mfma_f32_16x16x32_bf16 v[64:67], v[116:119], v[164:167], v[64:67]
	v_mfma_f32_16x16x32_bf16 v[60:63], v[132:135], v[164:167], v[60:63]
	v_mfma_f32_16x16x32_bf16 v[48:51], v[116:119], v[172:175], v[48:51]
	v_mfma_f32_16x16x32_bf16 v[44:47], v[132:135], v[172:175], v[44:47]
	v_mfma_f32_16x16x32_bf16 v[32:35], v[116:119], v[180:183], v[32:35]
	v_mfma_f32_16x16x32_bf16 v[28:31], v[132:135], v[180:183], v[28:31]
	v_mfma_f32_16x16x32_bf16 v[16:19], v[116:119], v[188:191], v[16:19]
	v_mfma_f32_16x16x32_bf16 v[12:15], v[132:135], v[188:191], v[12:15]
	v_mfma_f32_16x16x32_bf16 v[64:67], v[120:123], v[168:171], v[64:67]
	v_mfma_f32_16x16x32_bf16 v[60:63], v[136:139], v[168:171], v[60:63]
	v_mfma_f32_16x16x32_bf16 v[48:51], v[120:123], v[176:179], v[48:51]
	v_mfma_f32_16x16x32_bf16 v[44:47], v[136:139], v[176:179], v[44:47]
	v_mfma_f32_16x16x32_bf16 v[32:35], v[120:123], v[184:187], v[32:35]
	v_mfma_f32_16x16x32_bf16 v[28:31], v[136:139], v[184:187], v[28:31]
	v_mfma_f32_16x16x32_bf16 v[16:19], v[120:123], v[192:195], v[16:19]
	v_mfma_f32_16x16x32_bf16 v[12:15], v[136:139], v[192:195], v[12:15]
	s_setprio 0
	s_setprio 1
	v_mfma_f32_16x16x32_bf16 v[56:59], v[144:147], v[164:167], v[56:59]
	v_mfma_f32_16x16x32_bf16 v[52:55], v[156:159], v[164:167], v[52:55]
	v_mfma_f32_16x16x32_bf16 v[40:43], v[144:147], v[172:175], v[40:43]
	v_mfma_f32_16x16x32_bf16 v[36:39], v[156:159], v[172:175], v[36:39]
	v_mfma_f32_16x16x32_bf16 v[24:27], v[144:147], v[180:183], v[24:27]
	v_mfma_f32_16x16x32_bf16 v[20:23], v[156:159], v[180:183], v[20:23]
	v_mfma_f32_16x16x32_bf16 v[8:11], v[144:147], v[188:191], v[8:11]
	v_mfma_f32_16x16x32_bf16 v[4:7], v[156:159], v[188:191], v[4:7]
	v_mfma_f32_16x16x32_bf16 v[56:59], v[152:155], v[168:171], v[56:59]
	v_mfma_f32_16x16x32_bf16 v[52:55], v[160:163], v[168:171], v[52:55]
	v_mfma_f32_16x16x32_bf16 v[40:43], v[152:155], v[176:179], v[40:43]
	v_mfma_f32_16x16x32_bf16 v[36:39], v[160:163], v[176:179], v[36:39]
	v_mfma_f32_16x16x32_bf16 v[24:27], v[152:155], v[184:187], v[24:27]
	v_mfma_f32_16x16x32_bf16 v[20:23], v[160:163], v[184:187], v[20:23]
	v_mfma_f32_16x16x32_bf16 v[8:11], v[152:155], v[192:195], v[8:11]
	v_mfma_f32_16x16x32_bf16 v[4:7], v[160:163], v[192:195], v[4:7]
	s_setprio 0
	s_barrier
	s_add_i32 s66, 0, 0x18000
	s_add_i32 s67, 0, 0x1c000
	v_add_u32_e32 v136, s66, v226
	v_add_u32_e32 v160, s67, v226
	ds_read_b128 v[116:119], v136
	ds_read_b128 v[120:123], v136 offset:1024
	ds_read_b128 v[132:135], v136 offset:2048
	ds_read_b128 v[136:139], v136 offset:3072
	ds_read_b128 v[144:147], v160
	ds_read_b128 v[152:155], v160 offset:1024
	ds_read_b128 v[156:159], v160 offset:2048
	ds_read_b128 v[160:163], v160 offset:3072
	s_add_u32 s18, s24, 0xb0000
	s_addc_u32 s19, s25, 0
	s_mov_b32 m0, s36
	v_lshl_add_u64 v[248:249], s[18:19], 0, v[214:215]
	ds_read_b128 v[164:167], v228 offset:32768
	ds_read_b128 v[168:171], v228 offset:33792
	ds_read_b128 v[172:175], v228 offset:34816
	ds_read_b128 v[176:179], v228 offset:35840
	ds_read_b128 v[180:183], v228 offset:36864
	ds_read_b128 v[184:187], v228 offset:37888
	ds_read_b128 v[188:191], v228 offset:38912
	ds_read_b128 v[192:195], v228 offset:39936
	global_load_lds_dwordx4 v[248:249], off
	v_lshl_add_u64 v[248:249], s[18:19], 0, v[212:213]
	s_mov_b32 m0, s37
	s_nop 0
	global_load_lds_dwordx4 v[248:249], off
	s_waitcnt vmcnt(8)
	s_waitcnt lgkmcnt(0)
	s_barrier
	s_setprio 1
	s_waitcnt lgkmcnt(0)
	v_mfma_f32_16x16x32_bf16 v[148:151], v[116:119], v[164:167], v[148:151]
	v_mfma_f32_16x16x32_bf16 v[140:143], v[132:135], v[164:167], v[140:143]
	v_mfma_f32_16x16x32_bf16 v[112:115], v[116:119], v[172:175], v[112:115]
	v_mfma_f32_16x16x32_bf16 v[108:111], v[132:135], v[172:175], v[108:111]
	v_mfma_f32_16x16x32_bf16 v[96:99], v[116:119], v[180:183], v[96:99]
	v_mfma_f32_16x16x32_bf16 v[92:95], v[132:135], v[180:183], v[92:95]
	v_mfma_f32_16x16x32_bf16 v[80:83], v[116:119], v[188:191], v[80:83]
	v_mfma_f32_16x16x32_bf16 v[76:79], v[132:135], v[188:191], v[76:79]
	v_mfma_f32_16x16x32_bf16 v[148:151], v[120:123], v[168:171], v[148:151]
	v_mfma_f32_16x16x32_bf16 v[140:143], v[136:139], v[168:171], v[140:143]
	v_mfma_f32_16x16x32_bf16 v[112:115], v[120:123], v[176:179], v[112:115]
	v_mfma_f32_16x16x32_bf16 v[108:111], v[136:139], v[176:179], v[108:111]
	v_mfma_f32_16x16x32_bf16 v[96:99], v[120:123], v[184:187], v[96:99]
	v_mfma_f32_16x16x32_bf16 v[92:95], v[136:139], v[184:187], v[92:95]
	v_mfma_f32_16x16x32_bf16 v[80:83], v[120:123], v[192:195], v[80:83]
	v_mfma_f32_16x16x32_bf16 v[76:79], v[136:139], v[192:195], v[76:79]
	s_setprio 0
	s_setprio 1
	v_mfma_f32_16x16x32_bf16 v[128:131], v[144:147], v[164:167], v[128:131]
	v_mfma_f32_16x16x32_bf16 v[124:127], v[156:159], v[164:167], v[124:127]
	v_mfma_f32_16x16x32_bf16 v[104:107], v[144:147], v[172:175], v[104:107]
	v_mfma_f32_16x16x32_bf16 v[100:103], v[156:159], v[172:175], v[100:103]
	v_mfma_f32_16x16x32_bf16 v[88:91], v[144:147], v[180:183], v[88:91]
	v_mfma_f32_16x16x32_bf16 v[84:87], v[156:159], v[180:183], v[84:87]
	v_mfma_f32_16x16x32_bf16 v[72:75], v[144:147], v[188:191], v[72:75]
	v_mfma_f32_16x16x32_bf16 v[68:71], v[156:159], v[188:191], v[68:71]
	v_mfma_f32_16x16x32_bf16 v[128:131], v[152:155], v[168:171], v[128:131]
	v_mfma_f32_16x16x32_bf16 v[124:127], v[160:163], v[168:171], v[124:127]
	v_mfma_f32_16x16x32_bf16 v[104:107], v[152:155], v[176:179], v[104:107]
	v_mfma_f32_16x16x32_bf16 v[100:103], v[160:163], v[176:179], v[100:103]
	v_mfma_f32_16x16x32_bf16 v[88:91], v[152:155], v[184:187], v[88:91]
	v_mfma_f32_16x16x32_bf16 v[84:87], v[160:163], v[184:187], v[84:87]
	v_mfma_f32_16x16x32_bf16 v[72:75], v[152:155], v[192:195], v[72:75]
	v_mfma_f32_16x16x32_bf16 v[68:71], v[160:163], v[192:195], v[68:71]
	s_setprio 0
	s_barrier
; #define PG8_STAGE(bufoff, gbase, voff) do { _Pragma("unroll") for (int _i = 0; _i < 2; ++_i) \
;         __builtin_amdgcn_global_load_lds((const unsigned*)((const char*)(gbase) + (voff)[_i]), (PG8_LAS unsigned*)(lds + (bufoff) + ldsw + _i * 8192), 16, 0, 0); } while (0)
; #define PG8_LDA(dst, b, h) do { _Pragma("unroll") for (int m = 0; m < 4; ++m) _Pragma("unroll") for (int k = 0; k < 2; ++k) dst[m][k] = *(const PG8_LAS bf16x8*)(lds + PG8_SA(b, h) + aoff + m * 2048 + k * 1024); } while (0)
; #define PG8_MMA(ai, bj, At, Bt) do { __builtin_amdgcn_s_setprio(1); _Pragma("unroll") for (int m = 0; m < 4; ++m) _Pragma("unroll") for (int n = 0; n < 2; ++n) _Pragma("unroll") for (int k = 0; k < 2; ++k) \
;         acc[ai][bj][m][n] = __builtin_amdgcn_mfma_f32_16x16x32_bf16(Bt[n][k], At[m][k], acc[ai][bj][m][n], 0, 0, 0); __builtin_amdgcn_s_setprio(0); } while (0)
; #define PG8_WAIT_V(n) asm volatile("s_waitcnt vmcnt(" #n ")" ::: "memory")
; #define PG8_WAIT_L(n) asm volatile("s_waitcnt lgkmcnt(" #n ")" ::: "memory")
; #define PG8_BAR __builtin_amdgcn_s_barrier()
; #define PG8_SCHED __builtin_amdgcn_sched_barrier(0)
; template <class Epi, class Sched, bool ALIGN_EPI = false, bool SP2 = false>
; __device__ __forceinline__ void gemm_phase(PG8_LAS unsigned char* lds, const Gemm g, const Sched& S, const Epi& E) {
;     ...
;         for (int t = 0; t < nt; t += 2) {
;     ...
;             PG8_LDA(At, 1, 1); PG8_STAGE(PG8_SB(1, 0), b3, voffB); PG8_STAGE(PG8_SB(1, 1), b3 + hstep, voffB); PG8_STAGE(PG8_SA(1, 0), a3, voffA);
;             PG8_WAIT_V(8); PG8_WAIT_L(0); PG8_BAR; PG8_MMA(1, 0, At, B0); PG8_MMA(1, 1, At, B1); PG8_BAR; PG8_SCHED;
	s_add_i32 s18, s66, s31
	v_lshl_add_u64 v[220:221], v[220:221], 0, s[78:79]
	s_mov_b32 m0, s18
	ds_read_b128 v[164:167], v228 offset:49152
	ds_read_b128 v[168:171], v228 offset:50176
	ds_read_b128 v[172:175], v228 offset:51200
	ds_read_b128 v[176:179], v228 offset:52224
	ds_read_b128 v[180:183], v228 offset:53248
	ds_read_b128 v[184:187], v228 offset:54272
	ds_read_b128 v[188:191], v228 offset:55296
	ds_read_b128 v[192:195], v228 offset:56320
	global_load_lds_dwordx4 v[220:221], off
	s_add_i32 m0, s18, 0x2000
	s_add_u32 s18, s22, 0xb0080
	v_lshl_add_u64 v[220:221], v[222:223], 0, s[78:79]
	s_addc_u32 s19, s23, 0
	s_add_i32 s22, s67, s31
	global_load_lds_dwordx4 v[220:221], off
	v_lshl_add_u64 v[220:221], s[18:19], 0, v[196:197]
	s_mov_b32 m0, s22
	s_nop 0
	global_load_lds_dwordx4 v[220:221], off
	v_lshl_add_u64 v[220:221], s[18:19], 0, v[210:211]
	s_add_i32 m0, s22, 0x2000
	s_nop 0
	global_load_lds_dwordx4 v[220:221], off
	v_lshl_add_u64 v[220:221], v[224:225], 0, s[78:79]
	s_mov_b32 m0, s45
	s_nop 0
	global_load_lds_dwordx4 v[220:221], off
	v_lshl_add_u64 v[220:221], v[246:247], 0, s[78:79]
	s_mov_b32 m0, s48
	s_nop 0
	global_load_lds_dwordx4 v[220:221], off
	s_waitcnt vmcnt(8)
	s_waitcnt lgkmcnt(0)
	s_barrier
	s_setprio 1
	s_waitcnt lgkmcnt(0)
	v_mfma_f32_16x16x32_bf16 v[64:67], v[116:119], v[164:167], v[64:67]
	v_mfma_f32_16x16x32_bf16 v[60:63], v[132:135], v[164:167], v[60:63]
	v_mfma_f32_16x16x32_bf16 v[48:51], v[116:119], v[172:175], v[48:51]
	v_mfma_f32_16x16x32_bf16 v[44:47], v[132:135], v[172:175], v[44:47]
	v_mfma_f32_16x16x32_bf16 v[32:35], v[116:119], v[180:183], v[32:35]
	v_mfma_f32_16x16x32_bf16 v[28:31], v[132:135], v[180:183], v[28:31]
	v_mfma_f32_16x16x32_bf16 v[16:19], v[116:119], v[188:191], v[16:19]
	v_mfma_f32_16x16x32_bf16 v[12:15], v[132:135], v[188:191], v[12:15]
	v_mfma_f32_16x16x32_bf16 v[64:67], v[120:123], v[168:171], v[64:67]
	v_mfma_f32_16x16x32_bf16 v[60:63], v[136:139], v[168:171], v[60:63]
	v_mfma_f32_16x16x32_bf16 v[48:51], v[120:123], v[176:179], v[48:51]
	v_mfma_f32_16x16x32_bf16 v[44:47], v[136:139], v[176:179], v[44:47]
	v_mfma_f32_16x16x32_bf16 v[32:35], v[120:123], v[184:187], v[32:35]
	v_mfma_f32_16x16x32_bf16 v[28:31], v[136:139], v[184:187], v[28:31]
	v_mfma_f32_16x16x32_bf16 v[16:19], v[120:123], v[192:195], v[16:19]
	v_mfma_f32_16x16x32_bf16 v[12:15], v[136:139], v[192:195], v[12:15]
	s_setprio 0
	s_setprio 1
	v_mfma_f32_16x16x32_bf16 v[56:59], v[144:147], v[164:167], v[56:59]
	v_mfma_f32_16x16x32_bf16 v[52:55], v[156:159], v[164:167], v[52:55]
	v_mfma_f32_16x16x32_bf16 v[40:43], v[144:147], v[172:175], v[40:43]
	v_mfma_f32_16x16x32_bf16 v[36:39], v[156:159], v[172:175], v[36:39]
	v_mfma_f32_16x16x32_bf16 v[24:27], v[144:147], v[180:183], v[24:27]
	v_mfma_f32_16x16x32_bf16 v[20:23], v[156:159], v[180:183], v[20:23]
	v_mfma_f32_16x16x32_bf16 v[8:11], v[144:147], v[188:191], v[8:11]
	v_mfma_f32_16x16x32_bf16 v[4:7], v[156:159], v[188:191], v[4:7]
	v_mfma_f32_16x16x32_bf16 v[56:59], v[152:155], v[168:171], v[56:59]
	v_mfma_f32_16x16x32_bf16 v[52:55], v[160:163], v[168:171], v[52:55]
	v_mfma_f32_16x16x32_bf16 v[40:43], v[152:155], v[176:179], v[40:43]
	v_mfma_f32_16x16x32_bf16 v[36:39], v[160:163], v[176:179], v[36:39]
	v_mfma_f32_16x16x32_bf16 v[24:27], v[152:155], v[184:187], v[24:27]
	v_mfma_f32_16x16x32_bf16 v[20:23], v[160:163], v[184:187], v[20:23]
	v_mfma_f32_16x16x32_bf16 v[8:11], v[152:155], v[192:195], v[8:11]
	v_mfma_f32_16x16x32_bf16 v[4:7], v[160:163], v[192:195], v[4:7]
	s_setprio 0
	s_add_i32 s72, s72, 2
	s_add_u32 s64, s64, 0x100
	s_addc_u32 s65, s65, 0
	s_cmp_gt_u32 s72, 41
	s_mov_b64 s[18:19], s[20:21]
	s_barrier
	s_cbranch_scc0 .LBB0_1007
	s_and_b64 vcc, exec, s[14:15]
	s_cbranch_vccz .LBB0_1010
	s_barrier
